# v54 + MoE last-round row-half split: S=min(R,256-R) units of the last round run as two 128-row halves on two workgroups (half-unit K-loop copy skips the other half's MFMA blocks, stores exec-masked pe
# speedup vs baseline: 1.0039x; 1.0015x over previous
.LBB0_1717:
	s_or_b64 exec, exec, s[6:7]
	s_add_i32 s3, 0, 0x22080
	v_mov_b32_e32 v0, s3
	s_waitcnt lgkmcnt(0)
	s_barrier
	ds_read_b32 v0, v0
	s_load_dword s3, s[0:1], 0x230
	s_add_u32 s10, s0, 0x230
	s_addc_u32 s11, s1, 0
	v_readfirstlane_b32 s54, v209
	s_waitcnt lgkmcnt(0)
	v_cmp_ge_i32_e32 vcc, s2, v0
	v_readfirstlane_b32 s6, v0
	s_mov_b32 s92, s6
	s_lshr_b32 s93, s92, 8
	s_and_b32 s94, s92, 0xff
	s_sub_i32 s95, 0x100, s94
	s_min_u32 s95, s95, s94
	s_cmp_eq_u32 s3, 0x100
	s_cselect_b32 s93, s93, 0x7fffffff
	s_cmp_eq_u32 s93, 0
	s_cselect_b32 s93, 0x7fffffff, s93
	s_mov_b32 s90, 3
	s_mov_b32 s91, 3
	s_mov_b64 s[86:87], -1
	s_mov_b64 s[88:89], -1
	s_cbranch_vccnz .LBB0_1755
	s_ashr_i32 s7, s6, 31
	s_lshr_b32 s8, s7, 29
	s_add_i32 s8, s6, s8
	s_ashr_i32 s55, s8, 3
	s_and_b32 s8, s8, -8
	s_ashr_i32 s57, s2, 31
	s_sub_i32 s56, s6, s8
	s_lshr_b32 s8, s57, 29
	s_add_i32 s13, s2, s8
	s_and_b32 s8, s13, -8
	s_sub_i32 s12, s2, s8
	s_add_i32 s58, s55, 1
	s_cmp_ge_i32 s12, s56
	s_mul_i32 s59, s58, s56
	s_cbranch_scc0 .LBB0_1720
	s_sub_i32 s8, s12, s56
	s_mul_i32 s8, s8, s55
	s_add_i32 s20, s8, s59
	s_ashr_i32 s8, s13, 3
	s_cbranch_execz .LBB0_1721
	s_branch .LBB0_1722

.LBB0_1732:
	v_mul_f32_e32 v129, 0xbfb8aa3b, v124
	v_exp_f32_e32 v132, v129
	s_ashr_i32 s6, s82, 1
	v_add_u32_e32 v130, s6, v212
	v_add_u32_e32 v128, v198, v210
	v_add_f32_e32 v132, 1.0, v132
	v_rcp_f32_e32 v134, v132
	v_ashrrev_i32_e32 v129, 31, v128
	v_lshlrev_b64 v[128:129], 11, v[128:129]
	v_ashrrev_i32_e32 v131, 31, v130
	v_lshl_add_u64 v[128:129], s[14:15], 0, v[128:129]
	v_lshl_add_u64 v[128:129], v[130:131], 1, v[128:129]
	v_mul_f32_e32 v135, 0xbfb8aa3b, v125
	v_exp_f32_e32 v135, v135
	s_nop 0
	v_add_f32_e32 v133, 1.0, v135
	v_rcp_f32_e32 v136, v133
	v_mul_f32_e32 v130, v124, v134
	v_mov_b32_e32 v124, v130
	v_mul_f32_e32 v120, v124, v120
	v_mul_f32_e32 v131, 0xbfb8aa3b, v126
	v_exp_f32_e32 v131, v131
	v_mul_f32_e32 v124, v125, v136
	v_add_f32_e32 v130, 1.0, v131
	v_rcp_f32_e32 v132, v130
	v_mul_f32_e32 v121, v124, v121
	v_mul_f32_e32 v125, 0xbfb8aa3b, v127
	v_cvt_pk_bf16_f32 v120, v120, v121
	v_exp_f32_e32 v125, v125
	s_nop 0
	v_add_f32_e32 v125, 1.0, v125
	v_rcp_f32_e32 v133, v125
	v_mul_f32_e32 v121, v126, v132
	v_mul_f32_e32 v121, v121, v122
	v_mul_f32_e32 v126, 0xbfb8aa3b, v116
	v_exp_f32_e32 v126, v126
	v_mul_f32_e32 v122, v127, v133
	v_add_f32_e32 v124, 1.0, v126
	v_rcp_f32_e32 v126, v124
	v_mul_f32_e32 v122, v122, v123
	v_cvt_pk_bf16_f32 v121, v121, v122
	v_mul_f32_e32 v122, 0xbfb8aa3b, v117
	v_exp_f32_e32 v122, v122
	s_and_saveexec_b64 s[98:99], s[86:87]
	global_store_dwordx2 v[128:129], v[120:121], off
	s_mov_b64 exec, s[98:99]
	v_add_f32_e32 v122, 1.0, v122
	v_rcp_f32_e32 v125, v122
	v_mul_f32_e32 v120, v116, v126
	v_mov_b32_e32 v116, v120
	v_mul_f32_e32 v112, v116, v112
	v_mul_f32_e32 v121, 0xbfb8aa3b, v118
	v_exp_f32_e32 v121, v121
	v_mul_f32_e32 v116, v117, v125
	v_add_f32_e32 v120, 1.0, v121
	v_rcp_f32_e32 v123, v120
	v_mul_f32_e32 v113, v116, v113
	v_mul_f32_e32 v117, 0xbfb8aa3b, v119
	v_cvt_pk_bf16_f32 v112, v112, v113
	v_exp_f32_e32 v117, v117
	s_nop 0
	v_add_f32_e32 v117, 1.0, v117
	v_rcp_f32_e32 v122, v117
	v_mul_f32_e32 v113, v118, v123
	v_mul_f32_e32 v113, v113, v114
	v_mul_f32_e32 v118, 0xbfb8aa3b, v108
	v_exp_f32_e32 v118, v118
	v_mul_f32_e32 v114, v119, v122
	v_mul_f32_e32 v114, v114, v115
	v_add_f32_e32 v115, 1.0, v118
	v_rcp_f32_e32 v117, v115
	v_cvt_pk_bf16_f32 v113, v113, v114
	v_mul_f32_e32 v119, 0xbfb8aa3b, v109
	v_exp_f32_e32 v119, v119
	s_nop 0
	v_add_f32_e32 v116, 1.0, v119
	v_rcp_f32_e32 v120, v116
	v_mul_f32_e32 v114, v108, v117
	v_mov_b32_e32 v108, v114
	v_mul_f32_e32 v104, v108, v104
	v_mul_f32_e32 v115, 0xbfb8aa3b, v110
	v_exp_f32_e32 v115, v115
	v_mul_f32_e32 v108, v109, v120
	v_add_f32_e32 v114, 1.0, v115
	v_rcp_f32_e32 v117, v114
	v_mul_f32_e32 v105, v108, v105
	v_mul_f32_e32 v109, 0xbfb8aa3b, v111
	s_and_saveexec_b64 s[98:99], s[86:87]
	global_store_dwordx2 v[128:129], v[112:113], off offset:32
	s_mov_b64 exec, s[98:99]
	v_cvt_pk_bf16_f32 v104, v104, v105
	v_exp_f32_e32 v109, v109
	s_nop 0
	v_add_f32_e32 v109, 1.0, v109
	v_rcp_f32_e32 v116, v109
	v_mul_f32_e32 v105, v110, v117
	v_mul_f32_e32 v105, v105, v106
	v_mul_f32_e32 v106, v111, v116
	v_mul_f32_e32 v108, 0xbfb8aa3b, v100
	v_exp_f32_e32 v108, v108
	v_mul_f32_e32 v106, v106, v107
	v_cvt_pk_bf16_f32 v105, v105, v106
	v_add_f32_e32 v108, 1.0, v108
	v_rcp_f32_e32 v110, v108
	v_add_co_u32_e32 v106, vcc, s73, v128
	v_lshl_add_u64 v[112:113], v[128:129], 0, s[30:31]
	s_nop 0
	v_addc_co_u32_e32 v107, vcc, 0, v129, vcc
	s_and_saveexec_b64 s[98:99], s[86:87]
	global_store_dwordx2 v[106:107], v[104:105], off
	s_mov_b64 exec, s[98:99]
	v_mul_f32_e32 v106, 0xbfb8aa3b, v101
	v_exp_f32_e32 v106, v106
	s_nop 0
	v_add_f32_e32 v106, 1.0, v106
	v_rcp_f32_e32 v109, v106
	v_mul_f32_e32 v104, v100, v110
	v_mov_b32_e32 v100, v104
	v_mul_f32_e32 v96, v100, v96
	v_mul_f32_e32 v105, 0xbfb8aa3b, v102
	v_exp_f32_e32 v105, v105
	v_mul_f32_e32 v100, v101, v109
	v_add_f32_e32 v104, 1.0, v105
	v_rcp_f32_e32 v107, v104
	v_mul_f32_e32 v97, v100, v97
	v_mul_f32_e32 v101, 0xbfb8aa3b, v103
	v_cvt_pk_bf16_f32 v96, v96, v97
	v_exp_f32_e32 v101, v101
	s_nop 0
	v_add_f32_e32 v101, 1.0, v101
	v_rcp_f32_e32 v106, v101
	v_mul_f32_e32 v97, v102, v107
	v_mul_f32_e32 v97, v97, v98
	v_mul_f32_e32 v102, 0xbfb8aa3b, v92
	v_exp_f32_e32 v102, v102
	v_mul_f32_e32 v98, v103, v106
	v_mul_f32_e32 v98, v98, v99
	v_add_f32_e32 v99, 1.0, v102
	v_rcp_f32_e32 v101, v99
	v_cvt_pk_bf16_f32 v97, v97, v98
	v_mul_f32_e32 v103, 0xbfb8aa3b, v93
	v_exp_f32_e32 v103, v103
	s_nop 0
	v_add_f32_e32 v100, 1.0, v103
	v_rcp_f32_e32 v104, v100
	v_mul_f32_e32 v98, v92, v101
	v_mov_b32_e32 v92, v98
	v_mul_f32_e32 v88, v92, v88
	v_mul_f32_e32 v99, 0xbfb8aa3b, v94
	v_exp_f32_e32 v99, v99
	v_mul_f32_e32 v92, v93, v104
	v_add_f32_e32 v98, 1.0, v99
	v_rcp_f32_e32 v101, v98
	v_mul_f32_e32 v89, v92, v89
	v_mul_f32_e32 v93, 0xbfb8aa3b, v95
	s_and_saveexec_b64 s[98:99], s[86:87]
	global_store_dwordx2 v[112:113], v[96:97], off offset:32
	s_mov_b64 exec, s[98:99]
	v_cvt_pk_bf16_f32 v88, v88, v89
	v_exp_f32_e32 v93, v93
	s_nop 0
	v_add_f32_e32 v93, 1.0, v93
	v_rcp_f32_e32 v100, v93
	v_mul_f32_e32 v89, v94, v101
	v_mul_f32_e32 v89, v89, v90
	v_mul_f32_e32 v90, v95, v100
	v_mul_f32_e32 v92, 0xbfb8aa3b, v84
	v_exp_f32_e32 v92, v92
	v_mul_f32_e32 v90, v90, v91
	v_cvt_pk_bf16_f32 v89, v89, v90
	v_add_f32_e32 v92, 1.0, v92
	v_rcp_f32_e32 v94, v92
	v_add_co_u32_e32 v90, vcc, s69, v128
	v_lshl_add_u64 v[96:97], v[128:129], 0, s[34:35]
	s_nop 0
	v_addc_co_u32_e32 v91, vcc, 0, v129, vcc
	s_and_saveexec_b64 s[98:99], s[86:87]
	global_store_dwordx2 v[90:91], v[88:89], off
	s_mov_b64 exec, s[98:99]
	v_mul_f32_e32 v90, 0xbfb8aa3b, v85
	v_exp_f32_e32 v90, v90
	s_nop 0
	v_add_f32_e32 v90, 1.0, v90
	v_rcp_f32_e32 v93, v90
	v_mul_f32_e32 v88, v84, v94
	v_mov_b32_e32 v84, v88
	v_mul_f32_e32 v80, v84, v80
	v_mul_f32_e32 v89, 0xbfb8aa3b, v86
	v_exp_f32_e32 v89, v89
	v_mul_f32_e32 v84, v85, v93
	v_add_f32_e32 v88, 1.0, v89
	v_rcp_f32_e32 v91, v88
	v_mul_f32_e32 v81, v84, v81
	v_mul_f32_e32 v85, 0xbfb8aa3b, v87
	v_cvt_pk_bf16_f32 v80, v80, v81
	v_exp_f32_e32 v85, v85
	s_nop 0
	v_add_f32_e32 v85, 1.0, v85
	v_rcp_f32_e32 v90, v85
	v_mul_f32_e32 v81, v86, v91
	v_mul_f32_e32 v81, v81, v82
	v_mul_f32_e32 v86, 0xbfb8aa3b, v76
	v_exp_f32_e32 v86, v86
	v_mul_f32_e32 v82, v87, v90
	v_mul_f32_e32 v82, v82, v83
	v_add_f32_e32 v83, 1.0, v86
	v_rcp_f32_e32 v85, v83
	v_cvt_pk_bf16_f32 v81, v81, v82
	v_mul_f32_e32 v87, 0xbfb8aa3b, v77
	v_exp_f32_e32 v87, v87
	s_nop 0
	v_add_f32_e32 v84, 1.0, v87
	v_rcp_f32_e32 v88, v84
	v_mul_f32_e32 v82, v76, v85
	v_mov_b32_e32 v76, v82
	v_mul_f32_e32 v72, v76, v72
	v_mul_f32_e32 v83, 0xbfb8aa3b, v78
	v_exp_f32_e32 v83, v83
	v_mul_f32_e32 v76, v77, v88
	v_add_f32_e32 v82, 1.0, v83
	v_rcp_f32_e32 v85, v82
	v_mul_f32_e32 v73, v76, v73
	v_mul_f32_e32 v77, 0xbfb8aa3b, v79
	s_and_saveexec_b64 s[98:99], s[86:87]
	global_store_dwordx2 v[96:97], v[80:81], off offset:32
	s_mov_b64 exec, s[98:99]
	v_cvt_pk_bf16_f32 v72, v72, v73
	v_exp_f32_e32 v77, v77
	s_nop 0
	v_add_f32_e32 v77, 1.0, v77
	v_rcp_f32_e32 v84, v77
	v_mul_f32_e32 v73, v78, v85
	v_mul_f32_e32 v73, v73, v74
	v_mul_f32_e32 v74, v79, v84
	v_mul_f32_e32 v76, 0xbfb8aa3b, v68
	v_exp_f32_e32 v76, v76
	v_mul_f32_e32 v74, v74, v75
	v_cvt_pk_bf16_f32 v73, v73, v74
	v_add_f32_e32 v76, 1.0, v76
	v_rcp_f32_e32 v78, v76
	v_add_co_u32_e32 v74, vcc, s72, v128
	v_lshl_add_u64 v[80:81], v[128:129], 0, s[36:37]
	s_nop 0
	v_addc_co_u32_e32 v75, vcc, 0, v129, vcc
	s_and_saveexec_b64 s[98:99], s[86:87]
	global_store_dwordx2 v[74:75], v[72:73], off
	s_mov_b64 exec, s[98:99]
	v_mul_f32_e32 v74, 0xbfb8aa3b, v69
	v_exp_f32_e32 v74, v74
	s_nop 0
	v_add_f32_e32 v74, 1.0, v74
	v_rcp_f32_e32 v77, v74
	v_mul_f32_e32 v72, v68, v78
	v_mov_b32_e32 v68, v72
	v_mul_f32_e32 v64, v68, v64
	v_mul_f32_e32 v73, 0xbfb8aa3b, v70
	v_exp_f32_e32 v73, v73
	v_mul_f32_e32 v68, v69, v77
	v_add_f32_e32 v72, 1.0, v73
	v_rcp_f32_e32 v75, v72
	v_mul_f32_e32 v65, v68, v65
	v_mul_f32_e32 v69, 0xbfb8aa3b, v71
	v_cvt_pk_bf16_f32 v64, v64, v65
	v_exp_f32_e32 v69, v69
	s_nop 0
	v_add_f32_e32 v69, 1.0, v69
	v_rcp_f32_e32 v74, v69
	v_mul_f32_e32 v65, v70, v75
	v_mul_f32_e32 v65, v65, v66
	v_mul_f32_e32 v70, 0xbfb8aa3b, v60
	v_exp_f32_e32 v70, v70
	v_mul_f32_e32 v66, v71, v74
	v_mul_f32_e32 v66, v66, v67
	v_add_f32_e32 v67, 1.0, v70
	v_rcp_f32_e32 v69, v67
	v_cvt_pk_bf16_f32 v65, v65, v66
	v_mul_f32_e32 v71, 0xbfb8aa3b, v61
	v_exp_f32_e32 v71, v71
	s_nop 0
	v_add_f32_e32 v68, 1.0, v71
	v_rcp_f32_e32 v72, v68
	v_mul_f32_e32 v66, v60, v69
	v_mov_b32_e32 v60, v66
	v_mul_f32_e32 v56, v60, v56
	v_mul_f32_e32 v67, 0xbfb8aa3b, v62
	v_exp_f32_e32 v67, v67
	v_mul_f32_e32 v60, v61, v72
	v_add_f32_e32 v66, 1.0, v67
	v_rcp_f32_e32 v69, v66
	v_mul_f32_e32 v57, v60, v57
	v_mul_f32_e32 v61, 0xbfb8aa3b, v63
	s_and_saveexec_b64 s[98:99], s[86:87]
	global_store_dwordx2 v[80:81], v[64:65], off offset:32
	s_mov_b64 exec, s[98:99]
	v_cvt_pk_bf16_f32 v56, v56, v57
	v_exp_f32_e32 v61, v61
	s_nop 0
	v_add_f32_e32 v61, 1.0, v61
	v_rcp_f32_e32 v68, v61
	v_mul_f32_e32 v57, v62, v69
	v_mul_f32_e32 v57, v57, v58
	v_mul_f32_e32 v58, v63, v68
	v_mul_f32_e32 v60, 0xbfb8aa3b, v52
	v_exp_f32_e32 v60, v60
	v_mul_f32_e32 v58, v58, v59
	v_cvt_pk_bf16_f32 v57, v57, v58
	v_add_f32_e32 v60, 1.0, v60
	v_rcp_f32_e32 v62, v60
	v_add_co_u32_e32 v58, vcc, s78, v128
	v_lshl_add_u64 v[64:65], v[128:129], 0, s[42:43]
	s_nop 0
	v_addc_co_u32_e32 v59, vcc, 0, v129, vcc
	s_and_saveexec_b64 s[98:99], s[88:89]
	global_store_dwordx2 v[58:59], v[56:57], off
	s_mov_b64 exec, s[98:99]
	v_mul_f32_e32 v58, 0xbfb8aa3b, v53
	v_exp_f32_e32 v58, v58
	s_nop 0
	v_add_f32_e32 v58, 1.0, v58
	v_rcp_f32_e32 v61, v58
	v_mul_f32_e32 v56, v52, v62
	v_mov_b32_e32 v52, v56
	v_mul_f32_e32 v48, v52, v48
	v_mul_f32_e32 v57, 0xbfb8aa3b, v54
	v_exp_f32_e32 v57, v57
	v_mul_f32_e32 v52, v53, v61
	v_add_f32_e32 v56, 1.0, v57
	v_rcp_f32_e32 v59, v56
	v_mul_f32_e32 v49, v52, v49
	v_mul_f32_e32 v53, 0xbfb8aa3b, v55
	v_cvt_pk_bf16_f32 v48, v48, v49
	v_exp_f32_e32 v53, v53
	s_nop 0
	v_add_f32_e32 v53, 1.0, v53
	v_rcp_f32_e32 v58, v53
	v_mul_f32_e32 v49, v54, v59
	v_mul_f32_e32 v49, v49, v50
	v_mul_f32_e32 v54, 0xbfb8aa3b, v44
	v_exp_f32_e32 v54, v54
	v_mul_f32_e32 v50, v55, v58
	v_mul_f32_e32 v50, v50, v51
	v_add_f32_e32 v51, 1.0, v54
	v_rcp_f32_e32 v53, v51
	v_cvt_pk_bf16_f32 v49, v49, v50
	v_mul_f32_e32 v55, 0xbfb8aa3b, v45
	v_exp_f32_e32 v55, v55
	s_nop 0
	v_add_f32_e32 v52, 1.0, v55
	v_rcp_f32_e32 v56, v52
	v_mul_f32_e32 v50, v44, v53
	v_mov_b32_e32 v44, v50
	v_mul_f32_e32 v40, v44, v40
	v_mul_f32_e32 v51, 0xbfb8aa3b, v46
	v_exp_f32_e32 v51, v51
	v_mul_f32_e32 v44, v45, v56
	v_add_f32_e32 v50, 1.0, v51
	v_rcp_f32_e32 v53, v50
	v_mul_f32_e32 v41, v44, v41
	v_mul_f32_e32 v45, 0xbfb8aa3b, v47
	s_and_saveexec_b64 s[98:99], s[88:89]
	global_store_dwordx2 v[64:65], v[48:49], off offset:32
	s_mov_b64 exec, s[98:99]
	v_cvt_pk_bf16_f32 v40, v40, v41
	v_exp_f32_e32 v45, v45
	s_nop 0
	v_add_f32_e32 v45, 1.0, v45
	v_rcp_f32_e32 v52, v45
	v_mul_f32_e32 v41, v46, v53
	v_mul_f32_e32 v41, v41, v42
	v_mul_f32_e32 v42, v47, v52
	v_mul_f32_e32 v44, 0xbfb8aa3b, v36
	v_exp_f32_e32 v44, v44
	v_mul_f32_e32 v42, v42, v43
	v_cvt_pk_bf16_f32 v41, v41, v42
	v_add_f32_e32 v44, 1.0, v44
	v_rcp_f32_e32 v46, v44
	v_add_co_u32_e32 v42, vcc, s79, v128
	v_lshl_add_u64 v[48:49], v[128:129], 0, s[44:45]
	s_nop 0
	v_addc_co_u32_e32 v43, vcc, 0, v129, vcc
	s_and_saveexec_b64 s[98:99], s[88:89]
	global_store_dwordx2 v[42:43], v[40:41], off
	s_mov_b64 exec, s[98:99]
	v_mul_f32_e32 v42, 0xbfb8aa3b, v37
	v_exp_f32_e32 v42, v42
	s_nop 0
	v_add_f32_e32 v42, 1.0, v42
	v_rcp_f32_e32 v45, v42
	v_mul_f32_e32 v40, v36, v46
	v_mov_b32_e32 v36, v40
	v_mul_f32_e32 v32, v36, v32
	v_mul_f32_e32 v41, 0xbfb8aa3b, v38
	v_exp_f32_e32 v41, v41
	v_mul_f32_e32 v36, v37, v45
	v_add_f32_e32 v40, 1.0, v41
	v_rcp_f32_e32 v43, v40
	v_mul_f32_e32 v33, v36, v33
	v_mul_f32_e32 v37, 0xbfb8aa3b, v39
	v_cvt_pk_bf16_f32 v32, v32, v33
	v_exp_f32_e32 v37, v37
	s_nop 0
	v_add_f32_e32 v37, 1.0, v37
	v_rcp_f32_e32 v42, v37
	v_mul_f32_e32 v33, v38, v43
	v_mul_f32_e32 v33, v33, v34
	v_mul_f32_e32 v38, 0xbfb8aa3b, v28
	v_exp_f32_e32 v38, v38
	v_mul_f32_e32 v34, v39, v42
	v_mul_f32_e32 v34, v34, v35
	v_add_f32_e32 v35, 1.0, v38
	v_rcp_f32_e32 v37, v35
	v_cvt_pk_bf16_f32 v33, v33, v34
	v_mul_f32_e32 v39, 0xbfb8aa3b, v29
	v_exp_f32_e32 v39, v39
	s_nop 0
	v_add_f32_e32 v36, 1.0, v39
	v_rcp_f32_e32 v40, v36
	v_mul_f32_e32 v34, v28, v37
	v_mov_b32_e32 v28, v34
	v_mul_f32_e32 v24, v28, v24
	v_mul_f32_e32 v35, 0xbfb8aa3b, v30
	v_exp_f32_e32 v35, v35
	v_mul_f32_e32 v28, v29, v40
	v_add_f32_e32 v34, 1.0, v35
	v_rcp_f32_e32 v37, v34
	v_mul_f32_e32 v25, v28, v25
	v_mul_f32_e32 v29, 0xbfb8aa3b, v31
	s_and_saveexec_b64 s[98:99], s[88:89]
	global_store_dwordx2 v[48:49], v[32:33], off offset:32
	s_mov_b64 exec, s[98:99]
	v_cvt_pk_bf16_f32 v24, v24, v25
	v_exp_f32_e32 v29, v29
	s_nop 0
	v_add_f32_e32 v29, 1.0, v29
	v_rcp_f32_e32 v36, v29
	v_mul_f32_e32 v25, v30, v37
	v_mul_f32_e32 v25, v25, v26
	v_mul_f32_e32 v26, v31, v36
	v_mul_f32_e32 v28, 0xbfb8aa3b, v20
	v_exp_f32_e32 v28, v28
	v_mul_f32_e32 v26, v26, v27
	v_cvt_pk_bf16_f32 v25, v25, v26
	v_add_f32_e32 v28, 1.0, v28
	v_rcp_f32_e32 v30, v28
	v_add_co_u32_e32 v26, vcc, s80, v128
	v_lshl_add_u64 v[32:33], v[128:129], 0, s[46:47]
	s_nop 0
	v_addc_co_u32_e32 v27, vcc, 0, v129, vcc
	s_and_saveexec_b64 s[98:99], s[88:89]
	global_store_dwordx2 v[26:27], v[24:25], off
	s_mov_b64 exec, s[98:99]
	v_mul_f32_e32 v26, 0xbfb8aa3b, v21
	v_exp_f32_e32 v26, v26
	s_nop 0
	v_add_f32_e32 v26, 1.0, v26
	v_rcp_f32_e32 v29, v26
	v_mul_f32_e32 v24, v20, v30
	v_mov_b32_e32 v20, v24
	v_mul_f32_e32 v16, v20, v16
	v_mul_f32_e32 v25, 0xbfb8aa3b, v22
	v_exp_f32_e32 v25, v25
	v_mul_f32_e32 v20, v21, v29
	v_add_f32_e32 v24, 1.0, v25
	v_rcp_f32_e32 v27, v24
	v_mul_f32_e32 v17, v20, v17
	v_mul_f32_e32 v21, 0xbfb8aa3b, v23
	v_cvt_pk_bf16_f32 v16, v16, v17
	v_exp_f32_e32 v21, v21
	s_nop 0
	v_add_f32_e32 v21, 1.0, v21
	v_rcp_f32_e32 v26, v21
	v_mul_f32_e32 v17, v22, v27
	v_mul_f32_e32 v17, v17, v18
	v_mul_f32_e32 v22, 0xbfb8aa3b, v12
	v_exp_f32_e32 v22, v22
	v_mul_f32_e32 v18, v23, v26
	v_mul_f32_e32 v18, v18, v19
	v_add_f32_e32 v19, 1.0, v22
	v_rcp_f32_e32 v21, v19
	v_cvt_pk_bf16_f32 v17, v17, v18
	v_mul_f32_e32 v23, 0xbfb8aa3b, v13
	v_exp_f32_e32 v23, v23
	s_nop 0
	v_add_f32_e32 v20, 1.0, v23
	v_rcp_f32_e32 v24, v20
	v_mul_f32_e32 v18, v12, v21
	v_mov_b32_e32 v12, v18
	v_mul_f32_e32 v8, v12, v8
	v_mul_f32_e32 v19, 0xbfb8aa3b, v14
	v_exp_f32_e32 v19, v19
	v_mul_f32_e32 v12, v13, v24
	v_add_f32_e32 v18, 1.0, v19
	v_rcp_f32_e32 v21, v18
	v_mul_f32_e32 v9, v12, v9
	v_mul_f32_e32 v13, 0xbfb8aa3b, v15
	s_and_saveexec_b64 s[98:99], s[88:89]
	global_store_dwordx2 v[32:33], v[16:17], off offset:32
	s_mov_b64 exec, s[98:99]
	v_cvt_pk_bf16_f32 v8, v8, v9
	v_exp_f32_e32 v13, v13
	s_nop 0
	v_add_f32_e32 v13, 1.0, v13
	v_rcp_f32_e32 v20, v13
	v_mul_f32_e32 v9, v14, v21
	v_mul_f32_e32 v9, v9, v10
	v_mul_f32_e32 v10, v15, v20
	v_mul_f32_e32 v12, 0xbfb8aa3b, v4
	v_exp_f32_e32 v12, v12
	v_mul_f32_e32 v10, v10, v11
	v_cvt_pk_bf16_f32 v9, v9, v10
	v_add_f32_e32 v12, 1.0, v12
	v_rcp_f32_e32 v14, v12
	v_add_co_u32_e32 v10, vcc, s81, v128
	v_lshl_add_u64 v[16:17], v[128:129], 0, s[48:49]
	s_nop 0
	v_addc_co_u32_e32 v11, vcc, 0, v129, vcc
	s_and_saveexec_b64 s[98:99], s[88:89]
	global_store_dwordx2 v[10:11], v[8:9], off
	s_mov_b64 exec, s[98:99]
	v_mul_f32_e32 v10, 0xbfb8aa3b, v5
	v_exp_f32_e32 v10, v10
	s_nop 0
	v_add_f32_e32 v10, 1.0, v10
	v_rcp_f32_e32 v13, v10
	v_mul_f32_e32 v8, v4, v14
	v_mov_b32_e32 v4, v8
	v_mul_f32_e32 v0, v4, v0
	v_mul_f32_e32 v9, 0xbfb8aa3b, v6
	v_exp_f32_e32 v9, v9
	v_mul_f32_e32 v4, v5, v13
	v_add_f32_e32 v8, 1.0, v9
	v_rcp_f32_e32 v11, v8
	v_mul_f32_e32 v1, v4, v1
	v_mul_f32_e32 v5, 0xbfb8aa3b, v7
	v_cvt_pk_bf16_f32 v0, v0, v1
	v_exp_f32_e32 v5, v5
	s_nop 0
	v_add_f32_e32 v5, 1.0, v5
	v_rcp_f32_e32 v10, v5
	v_mul_f32_e32 v1, v6, v11
	v_mul_f32_e32 v1, v1, v2
	v_mul_f32_e32 v2, v7, v10
	v_mul_f32_e32 v2, v2, v3
	v_cvt_pk_bf16_f32 v1, v1, v2
	s_and_saveexec_b64 s[98:99], s[88:89]
	global_store_dwordx2 v[16:17], v[0:1], off offset:32
	s_mov_b64 exec, s[98:99]
	s_and_b64 vcc, exec, s[4:5]
	v_mov_b32_e32 v4, v180
	s_mov_b32 s82, s50
	v_mov_b32_e32 v198, v192
	v_mov_b64_e32 v[2:3], v[196:197]
	v_mov_b64_e32 v[0:1], v[194:195]
	s_mov_b32 s90, s91
	s_bitcmp1_b32 s90, 0
	s_cselect_b64 s[86:87], -1, 0
	s_bitcmp1_b32 s90, 1
	s_cselect_b64 s[88:89], -1, 0
	s_cbranch_vccnz .LBB0_1752
.LBB0_1733:
	s_add_i32 s68, s68, 1
	s_mul_i32 s4, s68, s74
	s_mul_hi_u32 s5, s68, s3
	s_add_i32 s5, s5, s4
	s_mul_i32 s4, s68, s3
	s_add_u32 s8, s4, s2
	s_addc_u32 s9, s5, s57
	s_mov_b32 s91, 3
	s_cmp_eq_u32 s68, s93
	s_cbranch_scc0 .Lts_done_a
	s_lshl_b32 s96, s95, 1
	s_cmp_lt_u32 s2, s96
	s_cbranch_scc0 .Lts_full_a
	s_and_b32 s97, s2, 1
	s_lshl_b32 s91, 1, s97
	s_lshr_b32 s96, s2, 1
	s_branch .Lts_set_a
.Lts_full_a:
	s_sub_i32 s96, s2, s95
	s_cmp_lt_u32 s96, s94
	s_cbranch_scc1 .Lts_set_a
	s_mov_b32 s8, s92
	s_branch .Lts_done_a
.Lts_set_a:
	s_lshl_b32 s97, s93, 8
	s_add_i32 s8, s97, s96
.Lts_done_a:
	v_cmp_ge_i64_e64 s[4:5], s[8:9], v[188:189]
	v_cmp_lt_i64_e64 s[6:7], s[8:9], v[188:189]
	s_and_b64 vcc, exec, s[4:5]
	s_cbranch_vccnz .LBB0_1746
	s_ashr_i32 s9, s8, 31
	s_lshr_b32 s9, s9, 29
	s_add_i32 s50, s8, s9
	s_and_b32 s9, s50, -8
	s_sub_i32 s51, s8, s9
	s_cmp_ge_i32 s51, s56
	s_mov_b64 s[8:9], -1
	s_cbranch_scc0 .LBB0_1736
	s_sub_i32 s8, s51, s56
	s_mul_i32 s8, s8, s55
	s_add_i32 s52, s8, s59
	s_mov_b64 s[8:9], 0

.LBB0_1746:
	v_lshl_add_u64 v[200:201], v[0:1], 0, s[24:25]
	v_mov_b32_e32 v0, 0
	v_add_u32_e32 v214, -1, v193
	v_lshl_add_u64 v[202:203], v[2:3], 0, s[28:29]
	s_mov_b32 s51, -2
	v_mov_b32_e32 v180, v4
	v_mov_b32_e32 v1, v0
	v_mov_b32_e32 v2, v0
	v_mov_b32_e32 v3, v0
	v_mov_b32_e32 v8, v0
	v_mov_b32_e32 v9, v0
	v_mov_b32_e32 v10, v0
	v_mov_b32_e32 v11, v0
	v_mov_b32_e32 v16, v0
	v_mov_b32_e32 v17, v0
	v_mov_b32_e32 v18, v0
	v_mov_b32_e32 v19, v0
	v_mov_b32_e32 v24, v0
	v_mov_b32_e32 v25, v0
	v_mov_b32_e32 v26, v0
	v_mov_b32_e32 v27, v0
	v_mov_b32_e32 v32, v0
	v_mov_b32_e32 v33, v0
	v_mov_b32_e32 v34, v0
	v_mov_b32_e32 v35, v0
	v_mov_b32_e32 v40, v0
	v_mov_b32_e32 v41, v0
	v_mov_b32_e32 v42, v0
	v_mov_b32_e32 v43, v0
	v_mov_b32_e32 v48, v0
	v_mov_b32_e32 v49, v0
	v_mov_b32_e32 v50, v0
	v_mov_b32_e32 v51, v0
	v_mov_b32_e32 v56, v0
	v_mov_b32_e32 v57, v0
	v_mov_b32_e32 v58, v0
	v_mov_b32_e32 v59, v0
	v_mov_b32_e32 v4, v0
	v_mov_b32_e32 v5, v0
	v_mov_b32_e32 v6, v0
	v_mov_b32_e32 v7, v0
	v_mov_b32_e32 v12, v0
	v_mov_b32_e32 v13, v0
	v_mov_b32_e32 v14, v0
	v_mov_b32_e32 v15, v0
	v_mov_b32_e32 v20, v0
	v_mov_b32_e32 v21, v0
	v_mov_b32_e32 v22, v0
	v_mov_b32_e32 v23, v0
	v_mov_b32_e32 v28, v0
	v_mov_b32_e32 v29, v0
	v_mov_b32_e32 v30, v0
	v_mov_b32_e32 v31, v0
	v_mov_b32_e32 v36, v0
	v_mov_b32_e32 v37, v0
	v_mov_b32_e32 v38, v0
	v_mov_b32_e32 v39, v0
	v_mov_b32_e32 v44, v0
	v_mov_b32_e32 v45, v0
	v_mov_b32_e32 v46, v0
	v_mov_b32_e32 v47, v0
	v_mov_b32_e32 v52, v0
	v_mov_b32_e32 v53, v0
	v_mov_b32_e32 v54, v0
	v_mov_b32_e32 v55, v0
	v_mov_b32_e32 v60, v0
	v_mov_b32_e32 v61, v0
	v_mov_b32_e32 v62, v0
	v_mov_b32_e32 v63, v0
	v_mov_b32_e32 v64, v0
	v_mov_b32_e32 v65, v0
	v_mov_b32_e32 v66, v0
	v_mov_b32_e32 v67, v0
	v_mov_b32_e32 v72, v0
	v_mov_b32_e32 v73, v0
	v_mov_b32_e32 v74, v0
	v_mov_b32_e32 v75, v0
	v_mov_b32_e32 v80, v0
	v_mov_b32_e32 v81, v0
	v_mov_b32_e32 v82, v0
	v_mov_b32_e32 v83, v0
	v_mov_b32_e32 v88, v0
	v_mov_b32_e32 v89, v0
	v_mov_b32_e32 v90, v0
	v_mov_b32_e32 v91, v0
	v_mov_b32_e32 v96, v0
	v_mov_b32_e32 v97, v0
	v_mov_b32_e32 v98, v0
	v_mov_b32_e32 v99, v0
	v_mov_b32_e32 v104, v0
	v_mov_b32_e32 v105, v0
	v_mov_b32_e32 v106, v0
	v_mov_b32_e32 v107, v0
	v_mov_b32_e32 v112, v0
	v_mov_b32_e32 v113, v0
	v_mov_b32_e32 v114, v0
	v_mov_b32_e32 v115, v0
	v_mov_b32_e32 v120, v0
	v_mov_b32_e32 v121, v0
	v_mov_b32_e32 v122, v0
	v_mov_b32_e32 v123, v0
	v_mov_b32_e32 v68, v0
	v_mov_b32_e32 v69, v0
	v_mov_b32_e32 v70, v0
	v_mov_b32_e32 v71, v0
	v_mov_b32_e32 v76, v0
	v_mov_b32_e32 v77, v0
	v_mov_b32_e32 v78, v0
	v_mov_b32_e32 v79, v0
	v_mov_b32_e32 v84, v0
	v_mov_b32_e32 v85, v0
	v_mov_b32_e32 v86, v0
	v_mov_b32_e32 v87, v0
	v_mov_b32_e32 v92, v0
	v_mov_b32_e32 v93, v0
	v_mov_b32_e32 v94, v0
	v_mov_b32_e32 v95, v0
	v_mov_b32_e32 v100, v0
	v_mov_b32_e32 v101, v0
	v_mov_b32_e32 v102, v0
	v_mov_b32_e32 v103, v0
	v_mov_b32_e32 v108, v0
	v_mov_b32_e32 v109, v0
	v_mov_b32_e32 v110, v0
	v_mov_b32_e32 v111, v0
	v_mov_b32_e32 v116, v0
	v_mov_b32_e32 v117, v0
	v_mov_b32_e32 v118, v0
	v_mov_b32_e32 v119, v0
	v_mov_b32_e32 v124, v0
	v_mov_b32_e32 v125, v0
	v_mov_b32_e32 v126, v0
	v_mov_b32_e32 v127, v0
	s_cmp_eq_u32 s90, 3
	s_cbranch_scc0 .Lts_a_h
	s_branch .LBB0_1749

.Lts_a_b:
	s_waitcnt lgkmcnt(8)
	s_barrier
	s_waitcnt lgkmcnt(0)
	v_lshl_add_u64 v[206:207], v[200:201], 0, s[24:25]
	v_cndmask_b32_e64 v233, v207, v195, s[8:9]
	v_cndmask_b32_e64 v232, v206, v194, s[8:9]
	v_cndmask_b32_e64 v207, v203, v197, s[8:9]
	v_cndmask_b32_e64 v206, v202, v196, s[8:9]
	s_setprio 1
	s_waitcnt lgkmcnt(0)
	s_bitcmp1_b32 s90, 0
	s_cbranch_scc0 .Lts_a_m0
	v_mfma_f32_16x16x32_bf16 v[124:127], v[128:131], v[168:171], v[124:127]
	v_mfma_f32_16x16x32_bf16 v[116:119], v[136:139], v[168:171], v[116:119]
	v_mfma_f32_16x16x32_bf16 v[108:111], v[128:131], v[160:163], v[108:111]
	v_mfma_f32_16x16x32_bf16 v[100:103], v[136:139], v[160:163], v[100:103]
	v_mfma_f32_16x16x32_bf16 v[92:95], v[128:131], v[152:155], v[92:95]
	v_mfma_f32_16x16x32_bf16 v[84:87], v[136:139], v[152:155], v[84:87]
	v_mfma_f32_16x16x32_bf16 v[76:79], v[128:131], v[144:147], v[76:79]
	v_mfma_f32_16x16x32_bf16 v[68:71], v[136:139], v[144:147], v[68:71]
	v_mfma_f32_16x16x32_bf16 v[124:127], v[132:135], v[172:175], v[124:127]
	v_mfma_f32_16x16x32_bf16 v[116:119], v[140:143], v[172:175], v[116:119]
	v_mfma_f32_16x16x32_bf16 v[108:111], v[132:135], v[164:167], v[108:111]
	v_mfma_f32_16x16x32_bf16 v[100:103], v[140:143], v[164:167], v[100:103]
	v_mfma_f32_16x16x32_bf16 v[92:95], v[132:135], v[156:159], v[92:95]
	v_mfma_f32_16x16x32_bf16 v[84:87], v[140:143], v[156:159], v[84:87]
	v_mfma_f32_16x16x32_bf16 v[76:79], v[132:135], v[148:151], v[76:79]
	v_mfma_f32_16x16x32_bf16 v[68:71], v[140:143], v[148:151], v[68:71]
.Lts_a_m0:
	s_setprio 0
	s_barrier
	s_mov_b32 m0, s62
	v_add_u32_e32 v185, s77, v211
	v_lshl_add_u64 v[234:235], v[206:207], 0, v[176:177]
	ds_read_b128 v[216:219], v185
	ds_read_b128 v[220:223], v185 offset:1024
	ds_read_b128 v[224:227], v185 offset:2048
	ds_read_b128 v[228:231], v185 offset:3072
	global_load_lds_dwordx4 v[234:235], off
	v_lshl_add_u64 v[236:237], v[206:207], 0, v[178:179]
	s_mov_b32 m0, s64
	s_nop 0
	global_load_lds_dwordx4 v[236:237], off
	s_barrier
	s_waitcnt lgkmcnt(0)
	s_setprio 1
	s_waitcnt lgkmcnt(0)
	s_bitcmp1_b32 s90, 0
	s_cbranch_scc0 .Lts_a_m1
	v_mfma_f32_16x16x32_bf16 v[120:123], v[216:219], v[168:171], v[120:123]
	v_mfma_f32_16x16x32_bf16 v[112:115], v[224:227], v[168:171], v[112:115]
	v_mfma_f32_16x16x32_bf16 v[104:107], v[216:219], v[160:163], v[104:107]
	v_mfma_f32_16x16x32_bf16 v[96:99], v[224:227], v[160:163], v[96:99]
	v_mfma_f32_16x16x32_bf16 v[88:91], v[216:219], v[152:155], v[88:91]
	v_mfma_f32_16x16x32_bf16 v[80:83], v[224:227], v[152:155], v[80:83]
	v_mfma_f32_16x16x32_bf16 v[72:75], v[216:219], v[144:147], v[72:75]
	v_mfma_f32_16x16x32_bf16 v[64:67], v[224:227], v[144:147], v[64:67]
	v_mfma_f32_16x16x32_bf16 v[120:123], v[220:223], v[172:175], v[120:123]
	v_mfma_f32_16x16x32_bf16 v[112:115], v[228:231], v[172:175], v[112:115]
	v_mfma_f32_16x16x32_bf16 v[104:107], v[220:223], v[164:167], v[104:107]
	v_mfma_f32_16x16x32_bf16 v[96:99], v[228:231], v[164:167], v[96:99]
	v_mfma_f32_16x16x32_bf16 v[88:91], v[220:223], v[156:159], v[88:91]
	v_mfma_f32_16x16x32_bf16 v[80:83], v[228:231], v[156:159], v[80:83]
	v_mfma_f32_16x16x32_bf16 v[72:75], v[220:223], v[148:151], v[72:75]
	v_mfma_f32_16x16x32_bf16 v[64:67], v[228:231], v[148:151], v[64:67]
.Lts_a_m1:
	s_setprio 0
	s_mov_b32 m0, s61
	v_readfirstlane_b32 s8, v232
	v_readfirstlane_b32 s9, v233
	s_barrier
	ds_read_b128 v[144:147], v213 offset:16384
	ds_read_b128 v[148:151], v213 offset:17408
	ds_read_b128 v[152:155], v213 offset:18432
	ds_read_b128 v[156:159], v213 offset:19456
	ds_read_b128 v[160:163], v213 offset:20480
	ds_read_b128 v[164:167], v213 offset:21504
	ds_read_b128 v[168:171], v213 offset:22528
	ds_read_b128 v[172:175], v213 offset:23552
	global_load_lds_dwordx4 v180, s[8:9]
	s_mov_b32 m0, s65
	v_mov_b32_e32 v185, v181
	global_load_lds_dwordx4 v184, s[8:9]
	s_barrier
	s_waitcnt lgkmcnt(0)
	v_lshl_add_u64 v[238:239], v[232:233], 0, v[180:181]
	v_lshl_add_u64 v[240:241], v[232:233], 0, v[184:185]
	s_setprio 1
	s_waitcnt lgkmcnt(0)
	s_bitcmp1_b32 s90, 1
	s_cbranch_scc0 .Lts_a_m2
	v_mfma_f32_16x16x32_bf16 v[60:63], v[128:131], v[144:147], v[60:63]
	v_mfma_f32_16x16x32_bf16 v[52:55], v[136:139], v[144:147], v[52:55]
	v_mfma_f32_16x16x32_bf16 v[44:47], v[128:131], v[152:155], v[44:47]
	v_mfma_f32_16x16x32_bf16 v[36:39], v[136:139], v[152:155], v[36:39]
	v_mfma_f32_16x16x32_bf16 v[28:31], v[128:131], v[160:163], v[28:31]
	v_mfma_f32_16x16x32_bf16 v[20:23], v[136:139], v[160:163], v[20:23]
	v_mfma_f32_16x16x32_bf16 v[12:15], v[128:131], v[168:171], v[12:15]
	v_mfma_f32_16x16x32_bf16 v[4:7], v[136:139], v[168:171], v[4:7]
	v_mfma_f32_16x16x32_bf16 v[60:63], v[132:135], v[148:151], v[60:63]
	v_mfma_f32_16x16x32_bf16 v[52:55], v[140:143], v[148:151], v[52:55]
	v_mfma_f32_16x16x32_bf16 v[44:47], v[132:135], v[156:159], v[44:47]
	v_mfma_f32_16x16x32_bf16 v[36:39], v[140:143], v[156:159], v[36:39]
	v_mfma_f32_16x16x32_bf16 v[28:31], v[132:135], v[164:167], v[28:31]
	v_mfma_f32_16x16x32_bf16 v[20:23], v[140:143], v[164:167], v[20:23]
	v_mfma_f32_16x16x32_bf16 v[12:15], v[132:135], v[172:175], v[12:15]
	v_mfma_f32_16x16x32_bf16 v[4:7], v[140:143], v[172:175], v[4:7]
.Lts_a_m2:
	s_setprio 0
	s_barrier
	v_lshl_add_u64 v[128:129], v[206:207], 0, s[22:23]
	s_add_i32 s8, s77, s60
	v_lshl_add_u64 v[130:131], v[128:129], 0, v[176:177]
	s_mov_b32 m0, s8
	v_lshl_add_u64 v[128:129], v[128:129], 0, v[178:179]
	global_load_lds_dwordx4 v[130:131], off
	s_add_i32 m0, s8, 0x2000
	s_nop 0
	global_load_lds_dwordx4 v[128:129], off
	s_waitcnt vmcnt(6)
	s_barrier
	s_setprio 1
	s_bitcmp1_b32 s90, 1
	s_cbranch_scc0 .Lts_a_m3
	v_mfma_f32_16x16x32_bf16 v[56:59], v[216:219], v[144:147], v[56:59]
	v_mfma_f32_16x16x32_bf16 v[48:51], v[224:227], v[144:147], v[48:51]
	v_mfma_f32_16x16x32_bf16 v[40:43], v[216:219], v[152:155], v[40:43]
	v_mfma_f32_16x16x32_bf16 v[32:35], v[224:227], v[152:155], v[32:35]
	v_mfma_f32_16x16x32_bf16 v[24:27], v[216:219], v[160:163], v[24:27]
	v_mfma_f32_16x16x32_bf16 v[16:19], v[224:227], v[160:163], v[16:19]
	v_mfma_f32_16x16x32_bf16 v[8:11], v[216:219], v[168:171], v[8:11]
	v_mfma_f32_16x16x32_bf16 v[0:3], v[224:227], v[168:171], v[0:3]
	v_mfma_f32_16x16x32_bf16 v[56:59], v[220:223], v[148:151], v[56:59]
	v_mfma_f32_16x16x32_bf16 v[48:51], v[228:231], v[148:151], v[48:51]
	v_mfma_f32_16x16x32_bf16 v[40:43], v[220:223], v[156:159], v[40:43]
	v_mfma_f32_16x16x32_bf16 v[32:35], v[228:231], v[156:159], v[32:35]
	v_mfma_f32_16x16x32_bf16 v[24:27], v[220:223], v[164:167], v[24:27]
	v_mfma_f32_16x16x32_bf16 v[16:19], v[228:231], v[164:167], v[16:19]
	v_mfma_f32_16x16x32_bf16 v[8:11], v[220:223], v[172:175], v[8:11]
	v_mfma_f32_16x16x32_bf16 v[0:3], v[228:231], v[172:175], v[0:3]
.Lts_a_m3:
	s_setprio 0
	s_add_i32 s8, 0, 0x18000
	v_add_u32_e32 v140, s8, v211
	s_barrier
	ds_read_b128 v[128:131], v140
	ds_read_b128 v[132:135], v140 offset:1024
	ds_read_b128 v[136:139], v140 offset:2048
	ds_read_b128 v[140:143], v140 offset:3072
	s_mov_b32 m0, s66
	v_lshl_add_u64 v[204:205], v[232:233], 0, v[204:205]
	ds_read_b128 v[144:147], v213 offset:32768
	ds_read_b128 v[148:151], v213 offset:33792
	ds_read_b128 v[152:155], v213 offset:34816
	ds_read_b128 v[156:159], v213 offset:35840
	ds_read_b128 v[160:163], v213 offset:36864
	ds_read_b128 v[164:167], v213 offset:37888
	ds_read_b128 v[168:171], v213 offset:38912
	ds_read_b128 v[172:175], v213 offset:39936
	global_load_lds_dwordx4 v[204:205], off
	v_lshl_add_u64 v[204:205], v[232:233], 0, v[182:183]
	s_mov_b32 m0, s67
	s_nop 0
	global_load_lds_dwordx4 v[204:205], off
	s_waitcnt lgkmcnt(8)
	s_barrier
	s_waitcnt lgkmcnt(0)
	s_setprio 1
	s_waitcnt lgkmcnt(0)
	s_bitcmp1_b32 s90, 0
	s_cbranch_scc0 .Lts_a_m4
	v_mfma_f32_16x16x32_bf16 v[124:127], v[128:131], v[144:147], v[124:127]
	v_mfma_f32_16x16x32_bf16 v[116:119], v[136:139], v[144:147], v[116:119]
	v_mfma_f32_16x16x32_bf16 v[108:111], v[128:131], v[152:155], v[108:111]
	v_mfma_f32_16x16x32_bf16 v[100:103], v[136:139], v[152:155], v[100:103]
	v_mfma_f32_16x16x32_bf16 v[92:95], v[128:131], v[160:163], v[92:95]
	v_mfma_f32_16x16x32_bf16 v[84:87], v[136:139], v[160:163], v[84:87]
	v_mfma_f32_16x16x32_bf16 v[76:79], v[128:131], v[168:171], v[76:79]
	v_mfma_f32_16x16x32_bf16 v[68:71], v[136:139], v[168:171], v[68:71]
	v_mfma_f32_16x16x32_bf16 v[124:127], v[132:135], v[148:151], v[124:127]
	v_mfma_f32_16x16x32_bf16 v[116:119], v[140:143], v[148:151], v[116:119]
	v_mfma_f32_16x16x32_bf16 v[108:111], v[132:135], v[156:159], v[108:111]
	v_mfma_f32_16x16x32_bf16 v[100:103], v[140:143], v[156:159], v[100:103]
	v_mfma_f32_16x16x32_bf16 v[92:95], v[132:135], v[164:167], v[92:95]
	v_mfma_f32_16x16x32_bf16 v[84:87], v[140:143], v[164:167], v[84:87]
	v_mfma_f32_16x16x32_bf16 v[76:79], v[132:135], v[172:175], v[76:79]
	v_mfma_f32_16x16x32_bf16 v[68:71], v[140:143], v[172:175], v[68:71]
.Lts_a_m4:
	s_setprio 0
	s_barrier
	s_add_i32 s9, 0, 0x1c000
	s_add_i32 s8, s8, s60
	v_add_u32_e32 v183, s9, v211
	v_lshl_add_u64 v[204:205], v[234:235], 0, s[24:25]
	s_mov_b32 m0, s8
	ds_read_b128 v[216:219], v183
	ds_read_b128 v[220:223], v183 offset:1024
	ds_read_b128 v[224:227], v183 offset:2048
	ds_read_b128 v[228:231], v183 offset:3072
	global_load_lds_dwordx4 v[204:205], off
	v_lshl_add_u64 v[204:205], v[236:237], 0, s[24:25]
	s_add_i32 m0, s8, 0x2000
	s_nop 0
	global_load_lds_dwordx4 v[204:205], off
	s_barrier
	s_waitcnt lgkmcnt(0)
	s_setprio 1
	s_waitcnt lgkmcnt(0)
	s_bitcmp1_b32 s90, 0
	s_cbranch_scc0 .Lts_a_m5
	v_mfma_f32_16x16x32_bf16 v[120:123], v[216:219], v[144:147], v[120:123]
	v_mfma_f32_16x16x32_bf16 v[112:115], v[224:227], v[144:147], v[112:115]
	v_mfma_f32_16x16x32_bf16 v[104:107], v[216:219], v[152:155], v[104:107]
	v_mfma_f32_16x16x32_bf16 v[96:99], v[224:227], v[152:155], v[96:99]
	v_mfma_f32_16x16x32_bf16 v[88:91], v[216:219], v[160:163], v[88:91]
	v_mfma_f32_16x16x32_bf16 v[80:83], v[224:227], v[160:163], v[80:83]
	v_mfma_f32_16x16x32_bf16 v[72:75], v[216:219], v[168:171], v[72:75]
	v_mfma_f32_16x16x32_bf16 v[64:67], v[224:227], v[168:171], v[64:67]
	v_mfma_f32_16x16x32_bf16 v[120:123], v[220:223], v[148:151], v[120:123]
	v_mfma_f32_16x16x32_bf16 v[112:115], v[228:231], v[148:151], v[112:115]
	v_mfma_f32_16x16x32_bf16 v[104:107], v[220:223], v[156:159], v[104:107]
	v_mfma_f32_16x16x32_bf16 v[96:99], v[228:231], v[156:159], v[96:99]
	v_mfma_f32_16x16x32_bf16 v[88:91], v[220:223], v[164:167], v[88:91]
	v_mfma_f32_16x16x32_bf16 v[80:83], v[228:231], v[164:167], v[80:83]
	v_mfma_f32_16x16x32_bf16 v[72:75], v[220:223], v[172:175], v[72:75]
	v_mfma_f32_16x16x32_bf16 v[64:67], v[228:231], v[172:175], v[64:67]
.Lts_a_m5:
	s_setprio 0
	s_mov_b32 m0, s70
	v_lshl_add_u64 v[204:205], v[238:239], 0, s[24:25]
	s_barrier
	ds_read_b128 v[144:147], v213 offset:49152
	ds_read_b128 v[148:151], v213 offset:50176
	ds_read_b128 v[152:155], v213 offset:51200
	ds_read_b128 v[156:159], v213 offset:52224
	ds_read_b128 v[160:163], v213 offset:53248
	ds_read_b128 v[164:167], v213 offset:54272
	ds_read_b128 v[168:171], v213 offset:55296
	ds_read_b128 v[172:175], v213 offset:56320
	global_load_lds_dwordx4 v[204:205], off
	v_lshl_add_u64 v[204:205], v[240:241], 0, s[24:25]
	s_mov_b32 m0, s71
	s_nop 0
	global_load_lds_dwordx4 v[204:205], off
	s_barrier
	s_waitcnt lgkmcnt(0)
	s_setprio 1
	s_waitcnt lgkmcnt(0)
	s_bitcmp1_b32 s90, 1
	s_cbranch_scc0 .Lts_a_m6
	v_mfma_f32_16x16x32_bf16 v[60:63], v[128:131], v[144:147], v[60:63]
	v_mfma_f32_16x16x32_bf16 v[52:55], v[136:139], v[144:147], v[52:55]
	v_mfma_f32_16x16x32_bf16 v[44:47], v[128:131], v[152:155], v[44:47]
	v_mfma_f32_16x16x32_bf16 v[36:39], v[136:139], v[152:155], v[36:39]
	v_mfma_f32_16x16x32_bf16 v[28:31], v[128:131], v[160:163], v[28:31]
	v_mfma_f32_16x16x32_bf16 v[20:23], v[136:139], v[160:163], v[20:23]
	v_mfma_f32_16x16x32_bf16 v[12:15], v[128:131], v[168:171], v[12:15]
	v_mfma_f32_16x16x32_bf16 v[4:7], v[136:139], v[168:171], v[4:7]
	v_mfma_f32_16x16x32_bf16 v[60:63], v[132:135], v[148:151], v[60:63]
	v_mfma_f32_16x16x32_bf16 v[52:55], v[140:143], v[148:151], v[52:55]
	v_mfma_f32_16x16x32_bf16 v[44:47], v[132:135], v[156:159], v[44:47]
	v_mfma_f32_16x16x32_bf16 v[36:39], v[140:143], v[156:159], v[36:39]
	v_mfma_f32_16x16x32_bf16 v[28:31], v[132:135], v[164:167], v[28:31]
	v_mfma_f32_16x16x32_bf16 v[20:23], v[140:143], v[164:167], v[20:23]
	v_mfma_f32_16x16x32_bf16 v[12:15], v[132:135], v[172:175], v[12:15]
	v_mfma_f32_16x16x32_bf16 v[4:7], v[140:143], v[172:175], v[4:7]
.Lts_a_m6:
	s_setprio 0
	s_barrier
	v_lshl_add_u64 v[128:129], v[206:207], 0, s[26:27]
	s_add_i32 s8, s9, s60
	v_lshl_add_u64 v[130:131], v[128:129], 0, v[176:177]
	s_mov_b32 m0, s8
	v_lshl_add_u64 v[128:129], v[128:129], 0, v[178:179]
	global_load_lds_dwordx4 v[130:131], off
	s_add_i32 m0, s8, 0x2000
	s_nop 0
	global_load_lds_dwordx4 v[128:129], off
	s_waitcnt vmcnt(6)
	s_barrier
	s_setprio 1
	s_bitcmp1_b32 s90, 1
	s_cbranch_scc0 .Lts_a_m7
	v_mfma_f32_16x16x32_bf16 v[56:59], v[216:219], v[144:147], v[56:59]
	v_mfma_f32_16x16x32_bf16 v[48:51], v[224:227], v[144:147], v[48:51]
	v_mfma_f32_16x16x32_bf16 v[40:43], v[216:219], v[152:155], v[40:43]
	v_mfma_f32_16x16x32_bf16 v[32:35], v[224:227], v[152:155], v[32:35]
	v_mfma_f32_16x16x32_bf16 v[24:27], v[216:219], v[160:163], v[24:27]
	v_mfma_f32_16x16x32_bf16 v[16:19], v[224:227], v[160:163], v[16:19]
	v_mfma_f32_16x16x32_bf16 v[8:11], v[216:219], v[168:171], v[8:11]
	v_mfma_f32_16x16x32_bf16 v[0:3], v[224:227], v[168:171], v[0:3]
	v_mfma_f32_16x16x32_bf16 v[56:59], v[220:223], v[148:151], v[56:59]
	v_mfma_f32_16x16x32_bf16 v[48:51], v[228:231], v[148:151], v[48:51]
	v_mfma_f32_16x16x32_bf16 v[40:43], v[220:223], v[156:159], v[40:43]
	v_mfma_f32_16x16x32_bf16 v[32:35], v[228:231], v[156:159], v[32:35]
	v_mfma_f32_16x16x32_bf16 v[24:27], v[220:223], v[164:167], v[24:27]
	v_mfma_f32_16x16x32_bf16 v[16:19], v[228:231], v[164:167], v[16:19]
	v_mfma_f32_16x16x32_bf16 v[8:11], v[220:223], v[172:175], v[8:11]
	v_mfma_f32_16x16x32_bf16 v[0:3], v[228:231], v[172:175], v[0:3]
.Lts_a_m7:
	s_setprio 0
	s_add_i32 s51, s51, 2
	v_lshl_add_u64 v[200:201], v[200:201], 0, s[28:29]
	s_cmp_gt_u32 s51, 29
	v_lshl_add_u64 v[202:203], v[202:203], 0, s[28:29]
	s_barrier
	s_cbranch_scc1 .LBB0_1732

.LBB0_1809:
	s_or_b64 exec, exec, s[6:7]
	s_add_i32 s3, 0, 0x22080
	v_mov_b32_e32 v0, s3
	s_waitcnt lgkmcnt(0)
	s_barrier
	ds_read_b32 v0, v0
	s_load_dword s3, s[0:1], 0x230
	s_add_u32 s6, s0, 0x230
	s_addc_u32 s7, s1, 0
	v_readfirstlane_b32 s46, v13
	s_waitcnt lgkmcnt(0)
	v_cmp_ge_i32_e32 vcc, s2, v0
	v_readfirstlane_b32 s20, v0
	s_mov_b32 s92, s20
	s_lshr_b32 s93, s92, 8
	s_and_b32 s94, s92, 0xff
	s_sub_i32 s95, 0x100, s94
	s_min_u32 s95, s95, s94
	s_cmp_eq_u32 s3, 0x100
	s_cselect_b32 s93, s93, 0x7fffffff
	s_cmp_eq_u32 s93, 0
	s_cselect_b32 s93, 0x7fffffff, s93
	s_mov_b32 s90, 3
	s_mov_b32 s91, 3
	s_mov_b64 s[86:87], -1
	s_mov_b64 s[88:89], -1
	s_cbranch_vccnz .LBB0_1837
	s_ashr_i32 s21, s20, 31
	s_lshr_b32 s8, s21, 29
	s_add_i32 s8, s20, s8
	s_ashr_i32 s47, s8, 3
	s_and_b32 s8, s8, -8
	s_ashr_i32 s49, s2, 31
	s_sub_i32 s48, s20, s8
	s_lshr_b32 s8, s49, 29
	s_add_i32 s11, s2, s8
	s_and_b32 s8, s11, -8
	s_sub_i32 s10, s2, s8
	s_add_i32 s50, s47, 1
	s_cmp_ge_i32 s10, s48
	s_mul_i32 s51, s50, s48
	s_cbranch_scc0 .LBB0_1812
	s_sub_i32 s8, s10, s48
	s_mul_i32 s8, s8, s47
	s_add_i32 s12, s8, s51
	s_load_dwordx2 s[14:15], s[4:5], 0x1d8
	s_ashr_i32 s13, s11, 3
	s_cbranch_execz .LBB0_1813
	s_branch .LBB0_1814

.LBB0_1821:
	s_add_i32 s57, s57, 1
	s_mul_i32 s4, s57, s61
	s_mul_hi_u32 s5, s57, s3
	s_add_i32 s5, s5, s4
	s_mul_i32 s4, s57, s3
	s_add_u32 s44, s4, s2
	s_addc_u32 s45, s5, s49
	s_mov_b32 s91, 3
	s_cmp_eq_u32 s57, s93
	s_cbranch_scc0 .Lts_done_b
	s_lshl_b32 s96, s95, 1
	s_cmp_lt_u32 s2, s96
	s_cbranch_scc0 .Lts_full_b
	s_and_b32 s97, s2, 1
	s_lshl_b32 s91, 1, s97
	s_lshr_b32 s96, s2, 1
	s_branch .Lts_set_b
.Lts_full_b:
	s_sub_i32 s96, s2, s95
	s_cmp_lt_u32 s96, s94
	s_cbranch_scc1 .Lts_set_b
	s_mov_b32 s44, s92
	s_branch .Lts_done_b
.Lts_set_b:
	s_lshl_b32 s97, s93, 8
	s_add_i32 s44, s97, s96
.Lts_done_b:
	v_cmp_ge_i64_e64 s[4:5], s[44:45], v[138:139]
	s_and_b64 vcc, exec, s[4:5]
	s_cbranch_vccnz .LBB0_1831
	s_ashr_i32 s45, s44, 31
	s_lshr_b32 s45, s45, 29
	s_add_i32 s73, s44, s45
	s_and_b32 s45, s73, -8
	s_sub_i32 s75, s44, s45
	s_cmp_ge_i32 s75, s48
	s_mov_b64 s[44:45], -1
	s_cbranch_scc0 .LBB0_1824
	s_sub_i32 s44, s75, s48
	s_mul_i32 s44, s44, s47
	s_add_i32 s76, s44, s51
	s_mov_b64 s[44:45], 0

.LBB0_1831:
	v_lshl_add_u64 v[150:151], v[0:1], 0, s[20:21]
	v_mov_b32_e32 v0, 0
	v_lshl_add_u64 v[148:149], v[2:3], 0, s[18:19]
	s_mov_b32 s44, -2
	v_mov_b32_e32 v1, v0
	v_mov_b32_e32 v2, v0
	v_mov_b32_e32 v3, v0
	v_mov_b32_e32 v4, v0
	v_mov_b32_e32 v5, v0
	v_mov_b32_e32 v6, v0
	v_mov_b32_e32 v7, v0
	v_mov_b32_e32 v8, v0
	v_mov_b32_e32 v9, v0
	v_mov_b32_e32 v10, v0
	v_mov_b32_e32 v11, v0
	v_mov_b32_e32 v16, v0
	v_mov_b32_e32 v17, v0
	v_mov_b32_e32 v18, v0
	v_mov_b32_e32 v19, v0
	v_mov_b32_e32 v24, v0
	v_mov_b32_e32 v25, v0
	v_mov_b32_e32 v26, v0
	v_mov_b32_e32 v27, v0
	v_mov_b32_e32 v32, v0
	v_mov_b32_e32 v33, v0
	v_mov_b32_e32 v34, v0
	v_mov_b32_e32 v35, v0
	v_mov_b32_e32 v40, v0
	v_mov_b32_e32 v41, v0
	v_mov_b32_e32 v42, v0
	v_mov_b32_e32 v43, v0
	v_mov_b32_e32 v48, v0
	v_mov_b32_e32 v49, v0
	v_mov_b32_e32 v50, v0
	v_mov_b32_e32 v51, v0
	v_mov_b32_e32 v12, v0
	v_mov_b32_e32 v13, v0
	v_mov_b32_e32 v14, v0
	v_mov_b32_e32 v15, v0
	v_mov_b32_e32 v20, v0
	v_mov_b32_e32 v21, v0
	v_mov_b32_e32 v22, v0
	v_mov_b32_e32 v23, v0
	v_mov_b32_e32 v28, v0
	v_mov_b32_e32 v29, v0
	v_mov_b32_e32 v30, v0
	v_mov_b32_e32 v31, v0
	v_mov_b32_e32 v36, v0
	v_mov_b32_e32 v37, v0
	v_mov_b32_e32 v38, v0
	v_mov_b32_e32 v39, v0
	v_mov_b32_e32 v44, v0
	v_mov_b32_e32 v45, v0
	v_mov_b32_e32 v46, v0
	v_mov_b32_e32 v47, v0
	v_mov_b32_e32 v52, v0
	v_mov_b32_e32 v53, v0
	v_mov_b32_e32 v54, v0
	v_mov_b32_e32 v55, v0
	v_mov_b32_e32 v56, v0
	v_mov_b32_e32 v57, v0
	v_mov_b32_e32 v58, v0
	v_mov_b32_e32 v59, v0
	v_mov_b32_e32 v60, v0
	v_mov_b32_e32 v61, v0
	v_mov_b32_e32 v62, v0
	v_mov_b32_e32 v63, v0
	v_mov_b32_e32 v64, v0
	v_mov_b32_e32 v65, v0
	v_mov_b32_e32 v66, v0
	v_mov_b32_e32 v67, v0
	v_mov_b32_e32 v68, v0
	v_mov_b32_e32 v69, v0
	v_mov_b32_e32 v70, v0
	v_mov_b32_e32 v71, v0
	v_mov_b32_e32 v72, v0
	v_mov_b32_e32 v73, v0
	v_mov_b32_e32 v74, v0
	v_mov_b32_e32 v75, v0
	v_mov_b32_e32 v80, v0
	v_mov_b32_e32 v81, v0
	v_mov_b32_e32 v82, v0
	v_mov_b32_e32 v83, v0
	v_mov_b32_e32 v88, v0
	v_mov_b32_e32 v89, v0
	v_mov_b32_e32 v90, v0
	v_mov_b32_e32 v91, v0
	v_mov_b32_e32 v96, v0
	v_mov_b32_e32 v97, v0
	v_mov_b32_e32 v98, v0
	v_mov_b32_e32 v99, v0
	v_mov_b32_e32 v104, v0
	v_mov_b32_e32 v105, v0
	v_mov_b32_e32 v106, v0
	v_mov_b32_e32 v107, v0
	v_mov_b32_e32 v112, v0
	v_mov_b32_e32 v113, v0
	v_mov_b32_e32 v114, v0
	v_mov_b32_e32 v115, v0
	v_mov_b32_e32 v76, v0
	v_mov_b32_e32 v77, v0
	v_mov_b32_e32 v78, v0
	v_mov_b32_e32 v79, v0
	v_mov_b32_e32 v84, v0
	v_mov_b32_e32 v85, v0
	v_mov_b32_e32 v86, v0
	v_mov_b32_e32 v87, v0
	v_mov_b32_e32 v92, v0
	v_mov_b32_e32 v93, v0
	v_mov_b32_e32 v94, v0
	v_mov_b32_e32 v95, v0
	v_mov_b32_e32 v100, v0
	v_mov_b32_e32 v101, v0
	v_mov_b32_e32 v102, v0
	v_mov_b32_e32 v103, v0
	v_mov_b32_e32 v108, v0
	v_mov_b32_e32 v109, v0
	v_mov_b32_e32 v110, v0
	v_mov_b32_e32 v111, v0
	v_mov_b32_e32 v116, v0
	v_mov_b32_e32 v117, v0
	v_mov_b32_e32 v118, v0
	v_mov_b32_e32 v119, v0
	v_mov_b32_e32 v120, v0
	v_mov_b32_e32 v121, v0
	v_mov_b32_e32 v122, v0
	v_mov_b32_e32 v123, v0
	v_mov_b32_e32 v124, v0
	v_mov_b32_e32 v125, v0
	v_mov_b32_e32 v126, v0
	v_mov_b32_e32 v127, v0
	s_cmp_eq_u32 s90, 3
	s_cbranch_scc1 .LBB0_1832
.Lts_b_h:
	v_add_u32_e32 v128, s65, v155
	ds_read_b128 v[158:161], v128
	ds_read_b128 v[162:165], v128 offset:1024
	ds_read_b128 v[166:169], v128 offset:2048
	ds_read_b128 v[170:173], v128 offset:3072
	s_cmp_eq_u32 s44, 12
	v_lshl_add_u64 v[152:153], v[148:149], 0, s[22:23]
	s_cselect_b64 vcc, -1, 0
	v_cndmask_b32_e32 v207, v153, v147, vcc
	v_cndmask_b32_e32 v206, v152, v146, vcc
	v_cndmask_b32_e32 v153, v151, v145, vcc
	v_cndmask_b32_e32 v152, v150, v144, vcc
	v_lshl_add_u64 v[210:211], v[148:149], 0, v[134:135]
	s_add_i32 m0, s53, 0xc000
	ds_read_b128 v[174:177], v157
	ds_read_b128 v[178:181], v157 offset:1024
	ds_read_b128 v[182:185], v157 offset:2048
	ds_read_b128 v[186:189], v157 offset:3072
	ds_read_b128 v[190:193], v157 offset:4096
	ds_read_b128 v[194:197], v157 offset:5120
	ds_read_b128 v[198:201], v157 offset:6144
	ds_read_b128 v[202:205], v157 offset:7168
	global_load_lds_dwordx4 v[210:211], off
	v_lshl_add_u64 v[210:211], v[148:149], 0, v[136:137]
	s_add_i32 m0, s53, 0xe000
	s_nop 0
	global_load_lds_dwordx4 v[210:211], off
	s_waitcnt lgkmcnt(8)
	s_barrier
	s_waitcnt lgkmcnt(0)
	s_setprio 1
	s_waitcnt lgkmcnt(0)
	s_bitcmp1_b32 s90, 0
	s_cbranch_scc0 .Lts_b_m0
	v_mfma_f32_16x16x32_bf16 v[124:127], v[158:161], v[174:177], v[124:127]
	v_mfma_f32_16x16x32_bf16 v[120:123], v[166:169], v[174:177], v[120:123]
	v_mfma_f32_16x16x32_bf16 v[116:119], v[158:161], v[182:185], v[116:119]
	v_mfma_f32_16x16x32_bf16 v[108:111], v[166:169], v[182:185], v[108:111]
	v_mfma_f32_16x16x32_bf16 v[100:103], v[158:161], v[190:193], v[100:103]
	v_mfma_f32_16x16x32_bf16 v[92:95], v[166:169], v[190:193], v[92:95]
	v_mfma_f32_16x16x32_bf16 v[84:87], v[158:161], v[198:201], v[84:87]
	v_mfma_f32_16x16x32_bf16 v[76:79], v[166:169], v[198:201], v[76:79]
	v_mfma_f32_16x16x32_bf16 v[124:127], v[162:165], v[178:181], v[124:127]
	v_mfma_f32_16x16x32_bf16 v[120:123], v[170:173], v[178:181], v[120:123]
	v_mfma_f32_16x16x32_bf16 v[116:119], v[162:165], v[186:189], v[116:119]
	v_mfma_f32_16x16x32_bf16 v[108:111], v[170:173], v[186:189], v[108:111]
	v_mfma_f32_16x16x32_bf16 v[100:103], v[162:165], v[194:197], v[100:103]
	v_mfma_f32_16x16x32_bf16 v[92:95], v[170:173], v[194:197], v[92:95]
	v_mfma_f32_16x16x32_bf16 v[84:87], v[162:165], v[202:205], v[84:87]
	v_mfma_f32_16x16x32_bf16 v[76:79], v[170:173], v[202:205], v[76:79]
.Lts_b_m0:
	s_setprio 0
	s_barrier
	s_add_i32 s45, s65, s52
	v_add_u32_e32 v128, s66, v155
	v_lshl_add_u64 v[226:227], v[152:153], 0, v[130:131]
	s_mov_b32 m0, s45
	ds_read_b128 v[210:213], v128
	ds_read_b128 v[214:217], v128 offset:1024
	ds_read_b128 v[218:221], v128 offset:2048
	ds_read_b128 v[222:225], v128 offset:3072
	global_load_lds_dwordx4 v[226:227], off
	v_lshl_add_u64 v[228:229], v[152:153], 0, v[132:133]
	s_add_i32 m0, s45, 0x2000
	s_nop 0
	global_load_lds_dwordx4 v[228:229], off
	s_barrier
	s_waitcnt lgkmcnt(0)
	s_setprio 1
	s_waitcnt lgkmcnt(0)
	s_bitcmp1_b32 s90, 0
	s_cbranch_scc0 .Lts_b_m1
	v_mfma_f32_16x16x32_bf16 v[112:115], v[210:213], v[174:177], v[112:115]
	v_mfma_f32_16x16x32_bf16 v[104:107], v[218:221], v[174:177], v[104:107]
	v_mfma_f32_16x16x32_bf16 v[96:99], v[210:213], v[182:185], v[96:99]
	v_mfma_f32_16x16x32_bf16 v[88:91], v[218:221], v[182:185], v[88:91]
	v_mfma_f32_16x16x32_bf16 v[80:83], v[210:213], v[190:193], v[80:83]
	v_mfma_f32_16x16x32_bf16 v[72:75], v[218:221], v[190:193], v[72:75]
	v_mfma_f32_16x16x32_bf16 v[68:71], v[210:213], v[198:201], v[68:71]
	v_mfma_f32_16x16x32_bf16 v[64:67], v[218:221], v[198:201], v[64:67]
	v_mfma_f32_16x16x32_bf16 v[112:115], v[214:217], v[178:181], v[112:115]
	v_mfma_f32_16x16x32_bf16 v[104:107], v[222:225], v[178:181], v[104:107]
	v_mfma_f32_16x16x32_bf16 v[96:99], v[214:217], v[186:189], v[96:99]
	v_mfma_f32_16x16x32_bf16 v[88:91], v[222:225], v[186:189], v[88:91]
	v_mfma_f32_16x16x32_bf16 v[80:83], v[214:217], v[194:197], v[80:83]
	v_mfma_f32_16x16x32_bf16 v[72:75], v[222:225], v[194:197], v[72:75]
	v_mfma_f32_16x16x32_bf16 v[68:71], v[214:217], v[202:205], v[68:71]
	v_mfma_f32_16x16x32_bf16 v[64:67], v[222:225], v[202:205], v[64:67]
.Lts_b_m1:
	s_setprio 0
	s_mov_b32 m0, s53
	v_lshl_add_u64 v[230:231], v[206:207], 0, v[130:131]
	s_barrier
	ds_read_b128 v[174:177], v157 offset:16384
	ds_read_b128 v[178:181], v157 offset:17408
	ds_read_b128 v[182:185], v157 offset:18432
	ds_read_b128 v[186:189], v157 offset:19456
	ds_read_b128 v[190:193], v157 offset:20480
	ds_read_b128 v[194:197], v157 offset:21504
	ds_read_b128 v[198:201], v157 offset:22528
	ds_read_b128 v[202:205], v157 offset:23552
	global_load_lds_dwordx4 v[230:231], off
	v_lshl_add_u64 v[232:233], v[206:207], 0, v[132:133]
	s_mov_b32 m0, s54
	s_nop 0
	global_load_lds_dwordx4 v[232:233], off
	s_barrier
	s_waitcnt lgkmcnt(0)
	s_setprio 1
	s_waitcnt lgkmcnt(0)
	s_bitcmp1_b32 s90, 1
	s_cbranch_scc0 .Lts_b_m2
	v_mfma_f32_16x16x32_bf16 v[60:63], v[158:161], v[174:177], v[60:63]
	v_mfma_f32_16x16x32_bf16 v[56:59], v[166:169], v[174:177], v[56:59]
	v_mfma_f32_16x16x32_bf16 v[52:55], v[158:161], v[182:185], v[52:55]
	v_mfma_f32_16x16x32_bf16 v[44:47], v[166:169], v[182:185], v[44:47]
	v_mfma_f32_16x16x32_bf16 v[36:39], v[158:161], v[190:193], v[36:39]
	v_mfma_f32_16x16x32_bf16 v[28:31], v[166:169], v[190:193], v[28:31]
	v_mfma_f32_16x16x32_bf16 v[20:23], v[158:161], v[198:201], v[20:23]
	v_mfma_f32_16x16x32_bf16 v[12:15], v[166:169], v[198:201], v[12:15]
	v_mfma_f32_16x16x32_bf16 v[60:63], v[162:165], v[178:181], v[60:63]
	v_mfma_f32_16x16x32_bf16 v[56:59], v[170:173], v[178:181], v[56:59]
	v_mfma_f32_16x16x32_bf16 v[52:55], v[162:165], v[186:189], v[52:55]
	v_mfma_f32_16x16x32_bf16 v[44:47], v[170:173], v[186:189], v[44:47]
	v_mfma_f32_16x16x32_bf16 v[36:39], v[162:165], v[194:197], v[36:39]
	v_mfma_f32_16x16x32_bf16 v[28:31], v[170:173], v[194:197], v[28:31]
	v_mfma_f32_16x16x32_bf16 v[20:23], v[162:165], v[202:205], v[20:23]
	v_mfma_f32_16x16x32_bf16 v[12:15], v[170:173], v[202:205], v[12:15]
.Lts_b_m2:
	s_setprio 0
	s_barrier
	v_lshl_add_u64 v[158:159], v[152:153], 0, s[12:13]
	s_add_i32 s45, s66, s52
	v_lshl_add_u64 v[160:161], v[158:159], 0, v[130:131]
	s_mov_b32 m0, s45
	v_lshl_add_u64 v[158:159], v[158:159], 0, v[132:133]
	global_load_lds_dwordx4 v[160:161], off
	s_add_i32 m0, s45, 0x2000
	s_nop 0
	global_load_lds_dwordx4 v[158:159], off
	s_waitcnt vmcnt(6)
	s_barrier
	s_setprio 1
	s_bitcmp1_b32 s90, 1
	s_cbranch_scc0 .Lts_b_m3
	v_mfma_f32_16x16x32_bf16 v[48:51], v[210:213], v[174:177], v[48:51]
	v_mfma_f32_16x16x32_bf16 v[40:43], v[218:221], v[174:177], v[40:43]
	v_mfma_f32_16x16x32_bf16 v[32:35], v[210:213], v[182:185], v[32:35]
	v_mfma_f32_16x16x32_bf16 v[24:27], v[218:221], v[182:185], v[24:27]
	v_mfma_f32_16x16x32_bf16 v[16:19], v[210:213], v[190:193], v[16:19]
	v_mfma_f32_16x16x32_bf16 v[8:11], v[218:221], v[190:193], v[8:11]
	v_mfma_f32_16x16x32_bf16 v[4:7], v[210:213], v[198:201], v[4:7]
	v_mfma_f32_16x16x32_bf16 v[0:3], v[218:221], v[198:201], v[0:3]
	v_mfma_f32_16x16x32_bf16 v[48:51], v[214:217], v[178:181], v[48:51]
	v_mfma_f32_16x16x32_bf16 v[40:43], v[222:225], v[178:181], v[40:43]
	v_mfma_f32_16x16x32_bf16 v[32:35], v[214:217], v[186:189], v[32:35]
	v_mfma_f32_16x16x32_bf16 v[24:27], v[222:225], v[186:189], v[24:27]
	v_mfma_f32_16x16x32_bf16 v[16:19], v[214:217], v[194:197], v[16:19]
	v_mfma_f32_16x16x32_bf16 v[8:11], v[222:225], v[194:197], v[8:11]
	v_mfma_f32_16x16x32_bf16 v[4:7], v[214:217], v[202:205], v[4:7]
	v_mfma_f32_16x16x32_bf16 v[0:3], v[222:225], v[202:205], v[0:3]
.Lts_b_m3:
	s_setprio 0
	s_add_i32 s45, 0, 0x18000
	v_add_u32_e32 v128, s45, v155
	s_barrier
	ds_read_b128 v[158:161], v128
	ds_read_b128 v[162:165], v128 offset:1024
	ds_read_b128 v[166:169], v128 offset:2048
	ds_read_b128 v[170:173], v128 offset:3072
	v_lshl_add_u64 v[206:207], v[206:207], 0, s[12:13]
	s_mov_b32 m0, s55
	v_lshl_add_u64 v[210:211], v[206:207], 0, v[130:131]
	ds_read_b128 v[174:177], v157 offset:32768
	ds_read_b128 v[178:181], v157 offset:33792
	ds_read_b128 v[182:185], v157 offset:34816
	ds_read_b128 v[186:189], v157 offset:35840
	ds_read_b128 v[190:193], v157 offset:36864
	ds_read_b128 v[194:197], v157 offset:37888
	ds_read_b128 v[198:201], v157 offset:38912
	ds_read_b128 v[202:205], v157 offset:39936
	global_load_lds_dwordx4 v[210:211], off
	v_lshl_add_u64 v[206:207], v[206:207], 0, v[132:133]
	s_mov_b32 m0, s56
	s_nop 0
	global_load_lds_dwordx4 v[206:207], off
	s_waitcnt lgkmcnt(8)
	s_barrier
	s_waitcnt lgkmcnt(0)
	s_setprio 1
	s_waitcnt lgkmcnt(0)
	s_bitcmp1_b32 s90, 0
	s_cbranch_scc0 .Lts_b_m4
	v_mfma_f32_16x16x32_bf16 v[124:127], v[158:161], v[174:177], v[124:127]
	v_mfma_f32_16x16x32_bf16 v[120:123], v[166:169], v[174:177], v[120:123]
	v_mfma_f32_16x16x32_bf16 v[116:119], v[158:161], v[182:185], v[116:119]
	v_mfma_f32_16x16x32_bf16 v[108:111], v[166:169], v[182:185], v[108:111]
	v_mfma_f32_16x16x32_bf16 v[100:103], v[158:161], v[190:193], v[100:103]
	v_mfma_f32_16x16x32_bf16 v[92:95], v[166:169], v[190:193], v[92:95]
	v_mfma_f32_16x16x32_bf16 v[84:87], v[158:161], v[198:201], v[84:87]
	v_mfma_f32_16x16x32_bf16 v[76:79], v[166:169], v[198:201], v[76:79]
	v_mfma_f32_16x16x32_bf16 v[124:127], v[162:165], v[178:181], v[124:127]
	v_mfma_f32_16x16x32_bf16 v[120:123], v[170:173], v[178:181], v[120:123]
	v_mfma_f32_16x16x32_bf16 v[116:119], v[162:165], v[186:189], v[116:119]
	v_mfma_f32_16x16x32_bf16 v[108:111], v[170:173], v[186:189], v[108:111]
	v_mfma_f32_16x16x32_bf16 v[100:103], v[162:165], v[194:197], v[100:103]
	v_mfma_f32_16x16x32_bf16 v[92:95], v[170:173], v[194:197], v[92:95]
	v_mfma_f32_16x16x32_bf16 v[84:87], v[162:165], v[202:205], v[84:87]
	v_mfma_f32_16x16x32_bf16 v[76:79], v[170:173], v[202:205], v[76:79]
.Lts_b_m4:
	s_setprio 0
	s_barrier
	s_add_i32 s75, 0, 0x1c000
	s_add_i32 s45, s45, s52
	v_add_u32_e32 v128, s75, v155
	v_lshl_add_u64 v[206:207], v[226:227], 0, s[16:17]
	s_mov_b32 m0, s45
	ds_read_b128 v[210:213], v128
	ds_read_b128 v[214:217], v128 offset:1024
	ds_read_b128 v[218:221], v128 offset:2048
	ds_read_b128 v[222:225], v128 offset:3072
	global_load_lds_dwordx4 v[206:207], off
	v_lshl_add_u64 v[206:207], v[228:229], 0, s[16:17]
	s_add_i32 m0, s45, 0x2000
	s_nop 0
	global_load_lds_dwordx4 v[206:207], off
	s_barrier
	s_waitcnt lgkmcnt(0)
	s_setprio 1
	s_waitcnt lgkmcnt(0)
	s_bitcmp1_b32 s90, 0
	s_cbranch_scc0 .Lts_b_m5
	v_mfma_f32_16x16x32_bf16 v[112:115], v[210:213], v[174:177], v[112:115]
	v_mfma_f32_16x16x32_bf16 v[104:107], v[218:221], v[174:177], v[104:107]
	v_mfma_f32_16x16x32_bf16 v[96:99], v[210:213], v[182:185], v[96:99]
	v_mfma_f32_16x16x32_bf16 v[88:91], v[218:221], v[182:185], v[88:91]
	v_mfma_f32_16x16x32_bf16 v[80:83], v[210:213], v[190:193], v[80:83]
	v_mfma_f32_16x16x32_bf16 v[72:75], v[218:221], v[190:193], v[72:75]
	v_mfma_f32_16x16x32_bf16 v[68:71], v[210:213], v[198:201], v[68:71]
	v_mfma_f32_16x16x32_bf16 v[64:67], v[218:221], v[198:201], v[64:67]
	v_mfma_f32_16x16x32_bf16 v[112:115], v[214:217], v[178:181], v[112:115]
	v_mfma_f32_16x16x32_bf16 v[104:107], v[222:225], v[178:181], v[104:107]
	v_mfma_f32_16x16x32_bf16 v[96:99], v[214:217], v[186:189], v[96:99]
	v_mfma_f32_16x16x32_bf16 v[88:91], v[222:225], v[186:189], v[88:91]
	v_mfma_f32_16x16x32_bf16 v[80:83], v[214:217], v[194:197], v[80:83]
	v_mfma_f32_16x16x32_bf16 v[72:75], v[222:225], v[194:197], v[72:75]
	v_mfma_f32_16x16x32_bf16 v[68:71], v[214:217], v[202:205], v[68:71]
	v_mfma_f32_16x16x32_bf16 v[64:67], v[222:225], v[202:205], v[64:67]
.Lts_b_m5:
	s_setprio 0
	s_mov_b32 m0, s59
	v_lshl_add_u64 v[206:207], v[230:231], 0, s[16:17]
	s_barrier
	ds_read_b128 v[174:177], v157 offset:49152
	ds_read_b128 v[178:181], v157 offset:50176
	ds_read_b128 v[182:185], v157 offset:51200
	ds_read_b128 v[186:189], v157 offset:52224
	ds_read_b128 v[190:193], v157 offset:53248
	ds_read_b128 v[194:197], v157 offset:54272
	ds_read_b128 v[198:201], v157 offset:55296
	ds_read_b128 v[202:205], v157 offset:56320
	global_load_lds_dwordx4 v[206:207], off
	v_lshl_add_u64 v[206:207], v[232:233], 0, s[16:17]
	s_mov_b32 m0, s60
	s_nop 0
	global_load_lds_dwordx4 v[206:207], off
	s_barrier
	s_waitcnt lgkmcnt(0)
	s_setprio 1
	s_waitcnt lgkmcnt(0)
	s_bitcmp1_b32 s90, 1
	s_cbranch_scc0 .Lts_b_m6
	v_mfma_f32_16x16x32_bf16 v[60:63], v[158:161], v[174:177], v[60:63]
	v_mfma_f32_16x16x32_bf16 v[56:59], v[166:169], v[174:177], v[56:59]
	v_mfma_f32_16x16x32_bf16 v[52:55], v[158:161], v[182:185], v[52:55]
	v_mfma_f32_16x16x32_bf16 v[44:47], v[166:169], v[182:185], v[44:47]
	v_mfma_f32_16x16x32_bf16 v[36:39], v[158:161], v[190:193], v[36:39]
	v_mfma_f32_16x16x32_bf16 v[28:31], v[166:169], v[190:193], v[28:31]
	v_mfma_f32_16x16x32_bf16 v[20:23], v[158:161], v[198:201], v[20:23]
	v_mfma_f32_16x16x32_bf16 v[12:15], v[166:169], v[198:201], v[12:15]
	v_mfma_f32_16x16x32_bf16 v[60:63], v[162:165], v[178:181], v[60:63]
	v_mfma_f32_16x16x32_bf16 v[56:59], v[170:173], v[178:181], v[56:59]
	v_mfma_f32_16x16x32_bf16 v[52:55], v[162:165], v[186:189], v[52:55]
	v_mfma_f32_16x16x32_bf16 v[44:47], v[170:173], v[186:189], v[44:47]
	v_mfma_f32_16x16x32_bf16 v[36:39], v[162:165], v[194:197], v[36:39]
	v_mfma_f32_16x16x32_bf16 v[28:31], v[170:173], v[194:197], v[28:31]
	v_mfma_f32_16x16x32_bf16 v[20:23], v[162:165], v[202:205], v[20:23]
	v_mfma_f32_16x16x32_bf16 v[12:15], v[170:173], v[202:205], v[12:15]
.Lts_b_m6:
	s_setprio 0
	s_barrier
	v_lshl_add_u64 v[152:153], v[152:153], 0, s[18:19]
	s_add_i32 s45, s75, s52
	v_lshl_add_u64 v[158:159], v[152:153], 0, v[130:131]
	s_mov_b32 m0, s45
	v_lshl_add_u64 v[152:153], v[152:153], 0, v[132:133]
	global_load_lds_dwordx4 v[158:159], off
	s_add_i32 m0, s45, 0x2000
	s_nop 0
	global_load_lds_dwordx4 v[152:153], off
	s_waitcnt vmcnt(6)
	s_barrier
	s_setprio 1
	s_bitcmp1_b32 s90, 1
	s_cbranch_scc0 .Lts_b_m7
	v_mfma_f32_16x16x32_bf16 v[48:51], v[210:213], v[174:177], v[48:51]
	v_mfma_f32_16x16x32_bf16 v[40:43], v[218:221], v[174:177], v[40:43]
	v_mfma_f32_16x16x32_bf16 v[32:35], v[210:213], v[182:185], v[32:35]
	v_mfma_f32_16x16x32_bf16 v[24:27], v[218:221], v[182:185], v[24:27]
	v_mfma_f32_16x16x32_bf16 v[16:19], v[210:213], v[190:193], v[16:19]
	v_mfma_f32_16x16x32_bf16 v[8:11], v[218:221], v[190:193], v[8:11]
	v_mfma_f32_16x16x32_bf16 v[4:7], v[210:213], v[198:201], v[4:7]
	v_mfma_f32_16x16x32_bf16 v[0:3], v[218:221], v[198:201], v[0:3]
	v_mfma_f32_16x16x32_bf16 v[48:51], v[214:217], v[178:181], v[48:51]
	v_mfma_f32_16x16x32_bf16 v[40:43], v[222:225], v[178:181], v[40:43]
	v_mfma_f32_16x16x32_bf16 v[32:35], v[214:217], v[186:189], v[32:35]
	v_mfma_f32_16x16x32_bf16 v[24:27], v[222:225], v[186:189], v[24:27]
	v_mfma_f32_16x16x32_bf16 v[16:19], v[214:217], v[194:197], v[16:19]
	v_mfma_f32_16x16x32_bf16 v[8:11], v[222:225], v[194:197], v[8:11]
	v_mfma_f32_16x16x32_bf16 v[4:7], v[214:217], v[202:205], v[4:7]
	v_mfma_f32_16x16x32_bf16 v[0:3], v[222:225], v[202:205], v[0:3]
.Lts_b_m7:
	s_setprio 0
	s_add_i32 s44, s44, 2
	v_lshl_add_u64 v[148:149], v[148:149], 0, s[20:21]
	s_cmp_gt_u32 s44, 13
	v_lshl_add_u64 v[150:151], v[150:151], 0, s[20:21]
	s_barrier
	s_cbranch_scc0 .Lts_b_h
	s_branch .Lts_b_x

.Lts_b_x:
	v_add_u32_e32 v140, v140, v154
	v_ashrrev_i32_e32 v141, 31, v140
	v_add_u32_e32 v148, s74, v156
	v_lshlrev_b64 v[140:141], 12, v[140:141]
	v_ashrrev_i32_e32 v149, 31, v148
	v_lshl_add_u64 v[140:141], s[14:15], 0, v[140:141]
	v_add_f32_e32 v124, 0, v124
	v_add_f32_e32 v125, 0, v125
	v_lshl_add_u64 v[140:141], v[148:149], 1, v[140:141]
	v_cvt_pk_bf16_f32 v124, v124, v125
	v_add_f32_e32 v125, 0, v126
	v_add_f32_e32 v120, 0, v120
	v_add_f32_e32 v121, 0, v121
	v_add_f32_e32 v126, 0, v127
	v_cvt_pk_bf16_f32 v125, v125, v126
	s_and_saveexec_b64 s[98:99], s[86:87]
	global_store_dwordx2 v[140:141], v[124:125], off
	s_mov_b64 exec, s[98:99]
	v_cvt_pk_bf16_f32 v120, v120, v121
	v_add_f32_e32 v121, 0, v122
	v_add_f32_e32 v112, 0, v112
	v_add_f32_e32 v113, 0, v113
	v_add_f32_e32 v122, 0, v123
	v_cvt_pk_bf16_f32 v121, v121, v122
	s_and_saveexec_b64 s[98:99], s[86:87]
	global_store_dwordx2 v[140:141], v[120:121], off offset:32
	s_mov_b64 exec, s[98:99]
	v_cvt_pk_bf16_f32 v112, v112, v113
	v_add_f32_e32 v113, 0, v114
	v_add_f32_e32 v104, 0, v104
	v_add_f32_e32 v105, 0, v105
	v_add_f32_e32 v114, 0, v115
	v_cvt_pk_bf16_f32 v113, v113, v114
	s_and_saveexec_b64 s[98:99], s[86:87]
	global_store_dwordx2 v[140:141], v[112:113], off offset:256
	s_mov_b64 exec, s[98:99]
	v_cvt_pk_bf16_f32 v104, v104, v105
	v_add_f32_e32 v105, 0, v106
	v_add_f32_e32 v106, 0, v107
	v_cvt_pk_bf16_f32 v105, v105, v106
	v_add_f32_e32 v106, 0, v116
	v_add_f32_e32 v107, 0, v117
	s_and_saveexec_b64 s[98:99], s[86:87]
	global_store_dwordx2 v[140:141], v[104:105], off offset:288
	s_mov_b64 exec, s[98:99]
	v_cvt_pk_bf16_f32 v106, v106, v107
	v_add_f32_e32 v107, 0, v118
	v_add_f32_e32 v112, 0, v119
	v_cvt_pk_bf16_f32 v107, v107, v112
	v_add_co_u32_e32 v112, vcc, s58, v140
	v_lshl_add_u64 v[104:105], v[140:141], 0, s[24:25]
	s_nop 0
	v_addc_co_u32_e32 v113, vcc, 0, v141, vcc
	s_and_saveexec_b64 s[98:99], s[86:87]
	global_store_dwordx2 v[112:113], v[106:107], off
	s_mov_b64 exec, s[98:99]
	v_add_f32_e32 v106, 0, v108
	v_add_f32_e32 v107, 0, v109
	v_cvt_pk_bf16_f32 v106, v106, v107
	v_add_f32_e32 v107, 0, v110
	v_add_f32_e32 v96, 0, v96
	v_add_f32_e32 v97, 0, v97
	v_add_f32_e32 v108, 0, v111
	v_cvt_pk_bf16_f32 v107, v107, v108
	s_and_saveexec_b64 s[98:99], s[86:87]
	global_store_dwordx2 v[104:105], v[106:107], off offset:32
	s_mov_b64 exec, s[98:99]
	v_cvt_pk_bf16_f32 v96, v96, v97
	v_add_f32_e32 v97, 0, v98
	v_add_f32_e32 v88, 0, v88
	v_add_f32_e32 v89, 0, v89
	v_add_f32_e32 v98, 0, v99
	v_cvt_pk_bf16_f32 v97, v97, v98
	s_and_saveexec_b64 s[98:99], s[86:87]
	global_store_dwordx2 v[104:105], v[96:97], off offset:256
	s_mov_b64 exec, s[98:99]
	v_cvt_pk_bf16_f32 v88, v88, v89
	v_add_f32_e32 v89, 0, v90
	v_add_f32_e32 v90, 0, v91
	v_cvt_pk_bf16_f32 v89, v89, v90
	v_add_f32_e32 v90, 0, v100
	v_add_f32_e32 v91, 0, v101
	s_and_saveexec_b64 s[98:99], s[86:87]
	global_store_dwordx2 v[104:105], v[88:89], off offset:288
	s_mov_b64 exec, s[98:99]
	v_cvt_pk_bf16_f32 v90, v90, v91
	v_add_f32_e32 v91, 0, v102
	v_add_f32_e32 v96, 0, v103
	v_cvt_pk_bf16_f32 v91, v91, v96
	v_add_co_u32_e32 v96, vcc, s67, v140
	v_lshl_add_u64 v[88:89], v[140:141], 0, s[26:27]
	s_nop 0
	v_addc_co_u32_e32 v97, vcc, 0, v141, vcc
	s_and_saveexec_b64 s[98:99], s[86:87]
	global_store_dwordx2 v[96:97], v[90:91], off
	s_mov_b64 exec, s[98:99]
	v_add_f32_e32 v90, 0, v92
	v_add_f32_e32 v91, 0, v93
	v_cvt_pk_bf16_f32 v90, v90, v91
	v_add_f32_e32 v91, 0, v94
	v_add_f32_e32 v80, 0, v80
	v_add_f32_e32 v81, 0, v81
	v_add_f32_e32 v92, 0, v95
	v_cvt_pk_bf16_f32 v91, v91, v92
	s_and_saveexec_b64 s[98:99], s[86:87]
	global_store_dwordx2 v[88:89], v[90:91], off offset:32
	s_mov_b64 exec, s[98:99]
	v_cvt_pk_bf16_f32 v80, v80, v81
	v_add_f32_e32 v81, 0, v82
	v_add_f32_e32 v72, 0, v72
	v_add_f32_e32 v73, 0, v73
	v_add_f32_e32 v82, 0, v83
	v_cvt_pk_bf16_f32 v81, v81, v82
	s_and_saveexec_b64 s[98:99], s[86:87]
	global_store_dwordx2 v[88:89], v[80:81], off offset:256
	s_mov_b64 exec, s[98:99]
	v_cvt_pk_bf16_f32 v72, v72, v73
	v_add_f32_e32 v73, 0, v74
	v_add_f32_e32 v74, 0, v75
	v_cvt_pk_bf16_f32 v73, v73, v74
	v_add_f32_e32 v74, 0, v84
	v_add_f32_e32 v75, 0, v85
	s_and_saveexec_b64 s[98:99], s[86:87]
	global_store_dwordx2 v[88:89], v[72:73], off offset:288
	s_mov_b64 exec, s[98:99]
	v_cvt_pk_bf16_f32 v74, v74, v75
	v_add_f32_e32 v75, 0, v86
	v_add_f32_e32 v80, 0, v87
	v_cvt_pk_bf16_f32 v75, v75, v80
	v_add_co_u32_e32 v80, vcc, s68, v140
	v_lshl_add_u64 v[72:73], v[140:141], 0, s[28:29]
	s_nop 0
	v_addc_co_u32_e32 v81, vcc, 0, v141, vcc
	s_and_saveexec_b64 s[98:99], s[86:87]
	global_store_dwordx2 v[80:81], v[74:75], off
	s_mov_b64 exec, s[98:99]
	v_add_f32_e32 v74, 0, v76
	v_add_f32_e32 v75, 0, v77
	v_cvt_pk_bf16_f32 v74, v74, v75
	v_add_f32_e32 v75, 0, v78
	v_add_f32_e32 v68, 0, v68
	v_add_f32_e32 v69, 0, v69
	v_add_f32_e32 v76, 0, v79
	v_cvt_pk_bf16_f32 v75, v75, v76
	s_and_saveexec_b64 s[98:99], s[86:87]
	global_store_dwordx2 v[72:73], v[74:75], off offset:32
	s_mov_b64 exec, s[98:99]
	v_cvt_pk_bf16_f32 v68, v68, v69
	v_add_f32_e32 v69, 0, v70
	v_add_f32_e32 v64, 0, v64
	v_add_f32_e32 v65, 0, v65
	v_add_f32_e32 v70, 0, v71
	v_cvt_pk_bf16_f32 v69, v69, v70
	s_and_saveexec_b64 s[98:99], s[86:87]
	global_store_dwordx2 v[72:73], v[68:69], off offset:256
	s_mov_b64 exec, s[98:99]
	v_cvt_pk_bf16_f32 v64, v64, v65
	v_add_f32_e32 v65, 0, v66
	v_add_f32_e32 v60, 0, v60
	v_add_f32_e32 v61, 0, v61
	v_add_f32_e32 v66, 0, v67
	v_cvt_pk_bf16_f32 v65, v65, v66
	s_and_saveexec_b64 s[98:99], s[86:87]
	global_store_dwordx2 v[72:73], v[64:65], off offset:288
	s_mov_b64 exec, s[98:99]
	v_cvt_pk_bf16_f32 v60, v60, v61
	v_add_f32_e32 v61, 0, v62
	v_add_f32_e32 v62, 0, v63
	v_cvt_pk_bf16_f32 v61, v61, v62
	v_add_co_u32_e32 v62, vcc, s69, v140
	v_add_f32_e32 v56, 0, v56
	s_nop 0
	v_addc_co_u32_e32 v63, vcc, 0, v141, vcc
	v_add_f32_e32 v57, 0, v57
	v_lshl_add_u64 v[64:65], v[140:141], 0, s[30:31]
	s_and_saveexec_b64 s[98:99], s[88:89]
	global_store_dwordx2 v[62:63], v[60:61], off
	s_mov_b64 exec, s[98:99]
	v_cvt_pk_bf16_f32 v56, v56, v57
	v_add_f32_e32 v57, 0, v58
	v_add_f32_e32 v48, 0, v48
	v_add_f32_e32 v49, 0, v49
	v_add_f32_e32 v58, 0, v59
	v_cvt_pk_bf16_f32 v57, v57, v58
	s_and_saveexec_b64 s[98:99], s[88:89]
	global_store_dwordx2 v[64:65], v[56:57], off offset:32
	s_mov_b64 exec, s[98:99]
	v_cvt_pk_bf16_f32 v48, v48, v49
	v_add_f32_e32 v49, 0, v50
	v_add_f32_e32 v40, 0, v40
	v_add_f32_e32 v41, 0, v41
	v_add_f32_e32 v50, 0, v51
	v_cvt_pk_bf16_f32 v49, v49, v50
	s_and_saveexec_b64 s[98:99], s[88:89]
	global_store_dwordx2 v[64:65], v[48:49], off offset:256
	s_mov_b64 exec, s[98:99]
	v_cvt_pk_bf16_f32 v40, v40, v41
	v_add_f32_e32 v41, 0, v42
	v_add_f32_e32 v42, 0, v43
	v_cvt_pk_bf16_f32 v41, v41, v42
	v_add_f32_e32 v42, 0, v52
	v_add_f32_e32 v43, 0, v53
	s_and_saveexec_b64 s[98:99], s[88:89]
	global_store_dwordx2 v[64:65], v[40:41], off offset:288
	s_mov_b64 exec, s[98:99]
	v_cvt_pk_bf16_f32 v42, v42, v43
	v_add_f32_e32 v43, 0, v54
	v_add_f32_e32 v48, 0, v55
	v_cvt_pk_bf16_f32 v43, v43, v48
	v_add_co_u32_e32 v48, vcc, s70, v140
	v_lshl_add_u64 v[40:41], v[140:141], 0, s[34:35]
	s_nop 0
	v_addc_co_u32_e32 v49, vcc, 0, v141, vcc
	s_and_saveexec_b64 s[98:99], s[88:89]
	global_store_dwordx2 v[48:49], v[42:43], off
	s_mov_b64 exec, s[98:99]
	v_add_f32_e32 v42, 0, v44
	v_add_f32_e32 v43, 0, v45
	v_cvt_pk_bf16_f32 v42, v42, v43
	v_add_f32_e32 v43, 0, v46
	v_add_f32_e32 v32, 0, v32
	v_add_f32_e32 v33, 0, v33
	v_add_f32_e32 v44, 0, v47
	v_cvt_pk_bf16_f32 v43, v43, v44
	s_and_saveexec_b64 s[98:99], s[88:89]
	global_store_dwordx2 v[40:41], v[42:43], off offset:32
	s_mov_b64 exec, s[98:99]
	v_cvt_pk_bf16_f32 v32, v32, v33
	v_add_f32_e32 v33, 0, v34
	v_add_f32_e32 v24, 0, v24
	v_add_f32_e32 v25, 0, v25
	v_add_f32_e32 v34, 0, v35
	v_cvt_pk_bf16_f32 v33, v33, v34
	s_and_saveexec_b64 s[98:99], s[88:89]
	global_store_dwordx2 v[40:41], v[32:33], off offset:256
	s_mov_b64 exec, s[98:99]
	v_cvt_pk_bf16_f32 v24, v24, v25
	v_add_f32_e32 v25, 0, v26
	v_add_f32_e32 v26, 0, v27
	v_cvt_pk_bf16_f32 v25, v25, v26
	v_add_f32_e32 v26, 0, v36
	v_add_f32_e32 v27, 0, v37
	s_and_saveexec_b64 s[98:99], s[88:89]
	global_store_dwordx2 v[40:41], v[24:25], off offset:288
	s_mov_b64 exec, s[98:99]
	v_cvt_pk_bf16_f32 v26, v26, v27
	v_add_f32_e32 v27, 0, v38
	v_add_f32_e32 v32, 0, v39
	v_cvt_pk_bf16_f32 v27, v27, v32
	v_add_co_u32_e32 v32, vcc, s71, v140
	v_lshl_add_u64 v[24:25], v[140:141], 0, s[36:37]
	s_nop 0
	v_addc_co_u32_e32 v33, vcc, 0, v141, vcc
	s_and_saveexec_b64 s[98:99], s[88:89]
	global_store_dwordx2 v[32:33], v[26:27], off
	s_mov_b64 exec, s[98:99]
	v_add_f32_e32 v26, 0, v28
	v_add_f32_e32 v27, 0, v29
	v_cvt_pk_bf16_f32 v26, v26, v27
	v_add_f32_e32 v27, 0, v30
	v_add_f32_e32 v16, 0, v16
	v_add_f32_e32 v17, 0, v17
	v_add_f32_e32 v28, 0, v31
	v_cvt_pk_bf16_f32 v27, v27, v28
	s_and_saveexec_b64 s[98:99], s[88:89]
	global_store_dwordx2 v[24:25], v[26:27], off offset:32
	s_mov_b64 exec, s[98:99]
	v_cvt_pk_bf16_f32 v16, v16, v17
	v_add_f32_e32 v17, 0, v18
	v_add_f32_e32 v8, 0, v8
	v_add_f32_e32 v9, 0, v9
	v_add_f32_e32 v18, 0, v19
	v_cvt_pk_bf16_f32 v17, v17, v18
	s_and_saveexec_b64 s[98:99], s[88:89]
	global_store_dwordx2 v[24:25], v[16:17], off offset:256
	s_mov_b64 exec, s[98:99]
	v_cvt_pk_bf16_f32 v8, v8, v9
	v_add_f32_e32 v9, 0, v10
	v_add_f32_e32 v10, 0, v11
	v_cvt_pk_bf16_f32 v9, v9, v10
	v_add_f32_e32 v10, 0, v20
	v_add_f32_e32 v11, 0, v21
	s_and_saveexec_b64 s[98:99], s[88:89]
	global_store_dwordx2 v[24:25], v[8:9], off offset:288
	s_mov_b64 exec, s[98:99]
	v_cvt_pk_bf16_f32 v10, v10, v11
	v_add_f32_e32 v11, 0, v22
	v_add_f32_e32 v16, 0, v23
	v_cvt_pk_bf16_f32 v11, v11, v16
	v_add_co_u32_e32 v16, vcc, s72, v140
	v_lshl_add_u64 v[8:9], v[140:141], 0, s[42:43]
	s_nop 0
	v_addc_co_u32_e32 v17, vcc, 0, v141, vcc
	s_and_saveexec_b64 s[98:99], s[88:89]
	global_store_dwordx2 v[16:17], v[10:11], off
	s_mov_b64 exec, s[98:99]
	v_add_f32_e32 v10, 0, v12
	v_add_f32_e32 v11, 0, v13
	v_cvt_pk_bf16_f32 v10, v10, v11
	v_add_f32_e32 v11, 0, v14
	v_add_f32_e32 v4, 0, v4
	v_add_f32_e32 v5, 0, v5
	v_add_f32_e32 v12, 0, v15
	v_cvt_pk_bf16_f32 v11, v11, v12
	s_and_saveexec_b64 s[98:99], s[88:89]
	global_store_dwordx2 v[8:9], v[10:11], off offset:32
	s_mov_b64 exec, s[98:99]
	v_cvt_pk_bf16_f32 v4, v4, v5
	v_add_f32_e32 v5, 0, v6
	v_add_f32_e32 v0, 0, v0
	v_add_f32_e32 v1, 0, v1
	v_add_f32_e32 v6, 0, v7
	v_cvt_pk_bf16_f32 v5, v5, v6
	s_and_saveexec_b64 s[98:99], s[88:89]
	global_store_dwordx2 v[8:9], v[4:5], off offset:256
	s_mov_b64 exec, s[98:99]
	v_cvt_pk_bf16_f32 v0, v0, v1
	v_add_f32_e32 v1, 0, v2
	v_add_f32_e32 v2, 0, v3
	v_cvt_pk_bf16_f32 v1, v1, v2
	s_and_saveexec_b64 s[98:99], s[88:89]
	global_store_dwordx2 v[8:9], v[0:1], off offset:288
	s_mov_b64 exec, s[98:99]
	s_and_b64 vcc, exec, s[4:5]
	s_mov_b32 s74, s73
	v_mov_b32_e32 v140, v142
	v_mov_b64_e32 v[0:1], v[144:145]
	v_mov_b64_e32 v[2:3], v[146:147]
	s_mov_b32 s90, s91
	s_bitcmp1_b32 s90, 0
	s_cselect_b64 s[86:87], -1, 0
	s_bitcmp1_b32 s90, 1
	s_cselect_b64 s[88:89], -1, 0
	s_cbranch_vccz .LBB0_1821
	s_waitcnt vmcnt(0)
	s_cmpk_gt_u32 s46, 0xff
	s_cbranch_scc1 .LBB0_1836
	s_barrier
